# FoX MFMA chains: half as many s_waitcnt lgkmcnt (one per two MFMAs, values tightened accordingly)
# speedup vs baseline: 1.0089x; 1.0049x over previous
; __device__ __forceinline__ void pv(f32x16 (&o)[2], const VFrags& v, const u32x4& pw0, const u32x4& pw1, const u32x4& pw2, const u32x4& pw3) {
;     ...
;     o[0] = __builtin_amdgcn_mfma_f32_32x32x16_bf16(__builtin_bit_cast(bf16x8, pw0), ATT_VF(0), o[0], 0, 0, 0);
;     o[1] = __builtin_amdgcn_mfma_f32_32x32x16_bf16(__builtin_bit_cast(bf16x8, pw0), ATT_VF(4), o[1], 0, 0, 0);
;     o[0] = __builtin_amdgcn_mfma_f32_32x32x16_bf16(__builtin_bit_cast(bf16x8, pw1), ATT_VF(1), o[0], 0, 0, 0);
;     o[1] = __builtin_amdgcn_mfma_f32_32x32x16_bf16(__builtin_bit_cast(bf16x8, pw1), ATT_VF(5), o[1], 0, 0, 0);
;     o[0] = __builtin_amdgcn_mfma_f32_32x32x16_bf16(__builtin_bit_cast(bf16x8, pw2), ATT_VF(2), o[0], 0, 0, 0);
;     o[1] = __builtin_amdgcn_mfma_f32_32x32x16_bf16(__builtin_bit_cast(bf16x8, pw2), ATT_VF(6), o[1], 0, 0, 0);
;     o[0] = __builtin_amdgcn_mfma_f32_32x32x16_bf16(__builtin_bit_cast(bf16x8, pw3), ATT_VF(3), o[0], 0, 0, 0);
;     o[1] = __builtin_amdgcn_mfma_f32_32x32x16_bf16(__builtin_bit_cast(bf16x8, pw3), ATT_VF(7), o[1], 0, 0, 0);
; __device__ __forceinline__ void fox_pair_pv(FoxState& st, const PairP& pp, lds_cptr vpB) {
;     { VFrags vf; vfrags(vf, vpB + 8192); pv(st.o, vf, pp.w[0], pp.w[1], pp.w[2], pp.w[3]); }
;     { VFrags vf; vfrags(vf, vpB); pv(st.o, vf, pp.w[4], pp.w[5], pp.w[6], pp.w[7]); }
; }
.LBB0_315:
	s_andn2_b64 vcc, exec, s[4:5]
	s_cbranch_vccnz .LBB0_317
	v_lshl_add_u32 v3, s1, 14, v180
	ds_read_b64_tr_b16 v[84:85], v3 offset:57344
	ds_read_b64_tr_b16 v[86:87], v3 offset:57856
	ds_read_b64_tr_b16 v[88:89], v3 offset:61440
	ds_read_b64_tr_b16 v[90:91], v3 offset:61952
	ds_read_b64_tr_b16 v[92:93], v3 offset:58368
	ds_read_b64_tr_b16 v[94:95], v3 offset:58880
	ds_read_b64_tr_b16 v[96:97], v3 offset:62464
	ds_read_b64_tr_b16 v[98:99], v3 offset:62976
	ds_read_b64_tr_b16 v[100:101], v3 offset:59392
	ds_read_b64_tr_b16 v[102:103], v3 offset:59904
	ds_read_b64_tr_b16 v[104:105], v3 offset:63488
	ds_read_b64_tr_b16 v[106:107], v3 offset:64000
	ds_read_b64_tr_b16 v[108:109], v3 offset:60416
	ds_read_b64_tr_b16 v[110:111], v3 offset:60928
	s_waitcnt lgkmcnt(10)
	v_mfma_f32_32x32x16_bf16 v[20:35], v[152:155], v[84:87], v[20:35]
	ds_read_b64_tr_b16 v[112:113], v3 offset:64512
	ds_read_b64_tr_b16 v[114:115], v3 offset:65024
	v_mfma_f32_32x32x16_bf16 v[36:51], v[152:155], v[88:91], v[36:51]
	ds_read_b64_tr_b16 v[84:85], v3 offset:49152
	ds_read_b64_tr_b16 v[86:87], v3 offset:49664
	s_waitcnt lgkmcnt(10)
	v_mfma_f32_32x32x16_bf16 v[20:35], v[148:151], v[92:95], v[20:35]
	ds_read_b64_tr_b16 v[88:89], v3 offset:53248
	ds_read_b64_tr_b16 v[90:91], v3 offset:53760
	v_mfma_f32_32x32x16_bf16 v[36:51], v[148:151], v[96:99], v[36:51]
	ds_read_b64_tr_b16 v[92:93], v3 offset:50176
	ds_read_b64_tr_b16 v[94:95], v3 offset:50688
	s_waitcnt lgkmcnt(10)
	v_mfma_f32_32x32x16_bf16 v[20:35], v[144:147], v[100:103], v[20:35]
	ds_read_b64_tr_b16 v[96:97], v3 offset:54272
	ds_read_b64_tr_b16 v[98:99], v3 offset:54784
	v_mfma_f32_32x32x16_bf16 v[36:51], v[144:147], v[104:107], v[36:51]
	ds_read_b64_tr_b16 v[100:101], v3 offset:51200
	ds_read_b64_tr_b16 v[102:103], v3 offset:51712
	s_waitcnt lgkmcnt(10)
	v_mfma_f32_32x32x16_bf16 v[20:35], v[140:143], v[108:111], v[20:35]
	ds_read_b64_tr_b16 v[104:105], v3 offset:55296
	ds_read_b64_tr_b16 v[106:107], v3 offset:55808
	v_mfma_f32_32x32x16_bf16 v[36:51], v[140:143], v[112:115], v[36:51]
	ds_read_b64_tr_b16 v[108:109], v3 offset:52224
	ds_read_b64_tr_b16 v[110:111], v3 offset:52736
	s_waitcnt lgkmcnt(10)
	v_mfma_f32_32x32x16_bf16 v[20:35], v[136:139], v[84:87], v[20:35]
	ds_read_b64_tr_b16 v[112:113], v3 offset:56320
	ds_read_b64_tr_b16 v[114:115], v3 offset:56832
	v_mfma_f32_32x32x16_bf16 v[36:51], v[136:139], v[88:91], v[36:51]
	s_waitcnt lgkmcnt(8)
	v_mfma_f32_32x32x16_bf16 v[20:35], v[132:135], v[92:95], v[20:35]
	v_mfma_f32_32x32x16_bf16 v[36:51], v[132:135], v[96:99], v[36:51]
	s_waitcnt lgkmcnt(4)
	v_mfma_f32_32x32x16_bf16 v[20:35], v[128:131], v[100:103], v[20:35]
	v_mfma_f32_32x32x16_bf16 v[36:51], v[128:131], v[104:107], v[36:51]
	s_waitcnt lgkmcnt(0)
	v_mfma_f32_32x32x16_bf16 v[20:35], v[124:127], v[108:111], v[20:35]
	v_mfma_f32_32x32x16_bf16 v[36:51], v[124:127], v[112:115], v[36:51]
.LBB0_317:
	s_add_i32 s80, s3, 0
	s_lshl_b32 s81, s90, 7
	v_add_u32_e32 v190, s3, v180
	s_cmp_ge_i32 s90, s89
	s_mov_b64 s[4:5], -1
	s_cbranch_scc0 .LBB0_328
	s_nop 11
	v_mov_b64_e32 v[66:67], v[50:51]
	v_mov_b64_e32 v[82:83], v[34:35]
	v_mov_b64_e32 v[162:163], v[158:159]
	s_cmp_lg_u32 s90, s89
	v_mov_b64_e32 v[64:65], v[48:49]
	v_mov_b64_e32 v[62:63], v[46:47]
	v_mov_b64_e32 v[60:61], v[44:45]
	v_mov_b64_e32 v[58:59], v[42:43]
	v_mov_b64_e32 v[56:57], v[40:41]
	v_mov_b64_e32 v[54:55], v[38:39]
	v_mov_b64_e32 v[52:53], v[36:37]
	v_mov_b64_e32 v[80:81], v[32:33]
	v_mov_b64_e32 v[78:79], v[30:31]
	v_mov_b64_e32 v[76:77], v[28:29]
	v_mov_b64_e32 v[74:75], v[26:27]
	v_mov_b64_e32 v[72:73], v[24:25]
	v_mov_b64_e32 v[70:71], v[22:23]
	v_mov_b64_e32 v[68:69], v[20:21]
	v_mov_b64_e32 v[160:161], v[156:157]
	v_mov_b32_e32 v194, v192
	v_mov_b32_e32 v191, v193
	s_cbranch_scc1 .LBB0_327
	v_lshl_add_u32 v196, s81, 2, v184
	s_andn2_b64 vcc, exec, s[94:95]
	v_add3_u32 v195, s80, v173, v188
	s_cbranch_vccnz .LBB0_325
	ds_read_b128 v[68:71], v196 offset:256
	ds_read_b128 v[72:75], v196 offset:288
	ds_read_b128 v[76:79], v196 offset:320
	ds_read_b128 v[80:83], v196 offset:352
	ds_read_b128 v[52:55], v196 offset:384
	ds_read_b128 v[56:59], v196 offset:416
	ds_read_b128 v[60:63], v196 offset:448
	ds_read_b128 v[64:67], v196 offset:480
	ds_read_b128 v[84:87], v195 offset:8192
	s_waitcnt lgkmcnt(5)
	v_mfma_f32_32x32x16_bf16 v[68:83], v[120:123], v[156:159], v[68:83]
	s_waitcnt lgkmcnt(0)
	v_mfma_f32_32x32x16_bf16 v[68:83], v[84:87], v[6:9], v[68:83]
	ds_read_b128 v[84:87], v195 offset:8704
	v_mfma_f32_32x32x16_bf16 v[52:67], v[120:123], v[156:159], v[52:67]
	s_waitcnt lgkmcnt(0)
	v_mfma_f32_32x32x16_bf16 v[52:67], v[84:87], v[6:9], v[52:67]
	ds_read_b128 v[84:87], v195 offset:10240
	s_waitcnt lgkmcnt(0)
	v_mfma_f32_32x32x16_bf16 v[68:83], v[84:87], v[10:13], v[68:83]
	ds_read_b128 v[84:87], v195 offset:10752
	s_waitcnt lgkmcnt(0)
	v_mfma_f32_32x32x16_bf16 v[52:67], v[84:87], v[10:13], v[52:67]
	ds_read_b128 v[84:87], v195 offset:12288
	s_waitcnt lgkmcnt(0)
	v_mfma_f32_32x32x16_bf16 v[68:83], v[84:87], v[14:17], v[68:83]
	ds_read_b128 v[84:87], v195 offset:12800
	s_waitcnt lgkmcnt(0)
	v_mfma_f32_32x32x16_bf16 v[52:67], v[84:87], v[14:17], v[52:67]
	ds_read_b128 v[84:87], v195 offset:14336
	s_waitcnt lgkmcnt(0)
	v_mfma_f32_32x32x16_bf16 v[68:83], v[84:87], v[116:119], v[68:83]
	ds_read_b128 v[84:87], v195 offset:14848
	s_waitcnt lgkmcnt(0)
; #define LAS __attribute__((address_space(3)))
; __device__ __forceinline__ int crow(int r, int hi) { return (r & 3) + 8 * (r >> 2) + 4 * hi; }
; __device__ __forceinline__ float swap_max(float m) { auto rr = __builtin_amdgcn_permlane32_swap(__float_as_uint(m), __float_as_uint(m), false, false); return fmaxf(__uint_as_float(rr[0]), __uint_as_float(rr[1])); }
; __device__ __forceinline__ float max3f(float a, float b, float c) { return __builtin_fmaxf(__builtin_fmaxf(a, b), c); }
; #define ATT_LDS_WAIT() asm volatile("s_waitcnt lgkmcnt(0)" ::: "memory")
;     ...
;     if (masked) {
;         asm volatile("; masked tile" ::: "memory");
; #pragma unroll
;         for (int r = 0; r < 16; ++r) { const int kv = crow(r, hi); if (kv >= qlim) p0[r] = NEG; if (kv + 32 >= qlim) p1[r] = NEG; }
;     }
;     float rm = max3f(p0[0], p1[0], p0[1]), rm2 = max3f(p1[1], p0[2], p1[2]);
; #pragma unroll
;     for (int r = 3; r < 15; r += 2) { rm = max3f(rm, p0[r], p1[r]); rm2 = max3f(rm2, p0[r + 1], p1[r + 1]); }
;     rm = max3f(rm, p0[15], p1[15]); rm = swap_max(max3f(rm, rm2, rm2));
;     if (first || __any(rm > FOX_THR)) {
;         const float dl = first ? rm : fmaxf(rm, 0.f);
;         st.m += dl; st.mq = make_mq(st.m, hi);
; #pragma unroll
;         for (int r = 0; r < 16; ++r) { p0[r] -= dl; p1[r] -= dl; }
;         if (!first) {
;             const float f = __builtin_amdgcn_exp2f(-dl);
;             st.l *= f;
;             if (hi == 0) wsf[r32] = f;
;             ATT_LDS_WAIT();
; #pragma unroll
;             for (int g = 0; g < 4; ++g) { const f32x4 fv = *(const LAS f32x4*)(wsf + 8 * g + 4 * hi);
; #pragma unroll
;                 for (int i = 0; i < 4; ++i) { st.o[0][4 * g + i] *= fv[i]; st.o[1][4 * g + i] *= fv[i]; } }
;         }
;     }
;     __builtin_amdgcn_sched_barrier(0);
;     VFrags vf; vfrags(vf, vp);
	v_mfma_f32_32x32x16_bf16 v[52:67], v[84:87], v[116:119], v[52:67]
	s_and_b64 vcc, s[70:71], s[66:67]
	s_nop 7
	v_cndmask_b32_e32 v82, v82, v18, vcc
	s_and_b64 vcc, vcc, s[62:63]
	v_cndmask_b32_e32 v81, v81, v18, vcc
	s_and_b64 vcc, vcc, s[58:59]
	v_cndmask_b32_e32 v80, v80, v18, vcc
	s_and_b64 vcc, vcc, s[54:55]
	v_cndmask_b32_e32 v79, v79, v18, vcc
	s_and_b64 vcc, vcc, s[50:51]
	v_cndmask_b32_e32 v78, v78, v18, vcc
	s_and_b64 vcc, vcc, s[46:47]
	v_cndmask_b32_e32 v77, v77, v18, vcc
	s_and_b64 vcc, vcc, s[42:43]
	v_cndmask_b32_e32 v76, v76, v18, vcc
	s_and_b64 vcc, vcc, s[38:39]
	v_cndmask_b32_e32 v75, v75, v18, vcc
	s_and_b64 vcc, vcc, s[34:35]
	v_cndmask_b32_e32 v74, v74, v18, vcc
	s_and_b64 vcc, vcc, s[28:29]
	v_cndmask_b32_e32 v73, v73, v18, vcc
	s_and_b64 vcc, vcc, s[24:25]
	v_cndmask_b32_e64 v3, v68, v18, s[8:9]
	v_cndmask_b32_e32 v72, v72, v18, vcc
	s_and_b64 vcc, vcc, s[20:21]
	v_cndmask_b32_e64 v3, v3, v68, s[12:13]
	v_cndmask_b32_e64 v4, v18, v69, s[12:13]
	v_cndmask_b32_e32 v71, v71, v18, vcc
	s_and_b64 vcc, vcc, s[16:17]
	v_cndmask_b32_e32 v69, v69, v4, vcc
	v_cndmask_b32_e32 v68, v68, v3, vcc
	v_cndmask_b32_e32 v70, v70, v18, vcc
	s_and_b64 vcc, s[72:73], s[68:69]
	v_cndmask_b32_e32 v66, v66, v18, vcc
	s_and_b64 vcc, vcc, s[64:65]
	v_cndmask_b32_e32 v65, v65, v18, vcc
	s_and_b64 vcc, vcc, s[60:61]
	v_cndmask_b32_e32 v64, v64, v18, vcc
	s_and_b64 vcc, vcc, s[56:57]
	v_cndmask_b32_e32 v63, v63, v18, vcc
	s_and_b64 vcc, vcc, s[52:53]
	v_cndmask_b32_e32 v62, v62, v18, vcc
	s_and_b64 vcc, vcc, s[48:49]
	v_cndmask_b32_e32 v61, v61, v18, vcc
	s_and_b64 vcc, vcc, s[44:45]
	v_cndmask_b32_e32 v60, v60, v18, vcc
	s_and_b64 vcc, vcc, s[40:41]
	v_cndmask_b32_e32 v59, v59, v18, vcc
	s_and_b64 vcc, vcc, s[36:37]
	v_cndmask_b32_e32 v58, v58, v18, vcc
	s_and_b64 vcc, vcc, s[30:31]
	v_cndmask_b32_e32 v57, v57, v18, vcc
	s_and_b64 vcc, vcc, s[26:27]
	v_cndmask_b32_e32 v56, v56, v18, vcc
	s_and_b64 vcc, vcc, s[22:23]
	v_cndmask_b32_e32 v55, v55, v18, vcc
	s_and_b64 vcc, vcc, s[18:19]
	v_cndmask_b32_e32 v54, v54, v18, vcc
	s_and_b64 vcc, vcc, s[14:15]
	v_cndmask_b32_e32 v53, v53, v18, vcc
	s_and_b64 vcc, vcc, s[10:11]
	v_cndmask_b32_e32 v52, v52, v18, vcc
	v_max_f32_e32 v3, v68, v68
	v_max_f32_e32 v4, v52, v52
	v_max_f32_e32 v3, v3, v4
	v_max3_f32 v4, v53, v70, v54
	v_max3_f32 v3, v3, v69, v71
	v_max3_f32 v4, v4, v72, v56
	v_max3_f32 v3, v3, v55, v73
	v_max3_f32 v4, v4, v74, v58
	v_max3_f32 v3, v3, v57, v75
	v_max3_f32 v4, v4, v76, v60
	v_max3_f32 v3, v3, v59, v77
	v_max3_f32 v4, v4, v78, v62
	v_max3_f32 v3, v3, v61, v79
	v_cndmask_b32_e64 v83, v83, v18, s[70:71]
	v_max3_f32 v4, v4, v80, v64
	v_max3_f32 v3, v3, v63, v81
	v_cndmask_b32_e64 v67, v67, v18, s[72:73]
	v_max3_f32 v4, v4, v82, v66
	v_max3_f32 v3, v3, v65, v83
	v_max3_f32 v3, v3, v67, v4
	v_mov_b32_e32 v4, v3
	s_nop 1
	v_permlane32_swap_b32_e32 v3, v4
	v_max_f32_e32 v4, v4, v4
	v_max_f32_e32 v3, v3, v3
	v_max_f32_e32 v84, v3, v4
	v_add_f32_e32 v191, v193, v84
	v_cvt_pk_bf16_f32 v3, v191, 0
	v_lshlrev_b32_e32 v3, 16, v3
	v_sub_f32_e32 v4, v191, v3
	v_cvt_pk_bf16_f32 v85, v4, 0
	v_lshlrev_b32_e32 v85, 16, v85
	v_sub_f32_e32 v4, v4, v85
	v_cvt_pk_bf16_f32 v3, 1.0, v3
	v_cvt_pk_bf16_f32 v4, v85, v4
	v_cndmask_b32_e64 v4, 0, v4, s[6:7]
	v_cndmask_b32_e64 v3, 0, v3, s[6:7]
	v_sub_f32_e32 v68, v68, v84
	v_sub_f32_e32 v112, v52, v84
	v_sub_f32_e32 v69, v69, v84
	v_sub_f32_e32 v113, v53, v84
	v_sub_f32_e32 v70, v70, v84
	v_sub_f32_e32 v114, v54, v84
	v_sub_f32_e32 v71, v71, v84
	v_sub_f32_e32 v115, v55, v84
	v_sub_f32_e32 v72, v72, v84
	v_sub_f32_e32 v56, v56, v84
	v_sub_f32_e32 v73, v73, v84
	v_sub_f32_e32 v57, v57, v84
	v_sub_f32_e32 v74, v74, v84
	v_sub_f32_e32 v58, v58, v84
	v_sub_f32_e32 v75, v75, v84
	v_sub_f32_e32 v59, v59, v84
	v_sub_f32_e32 v76, v76, v84
	v_sub_f32_e32 v60, v60, v84
	v_sub_f32_e32 v77, v77, v84
	v_sub_f32_e32 v61, v61, v84
	v_sub_f32_e32 v78, v78, v84
	v_sub_f32_e32 v62, v62, v84
	v_sub_f32_e32 v79, v79, v84
	v_sub_f32_e32 v63, v63, v84
	v_sub_f32_e32 v80, v80, v84
	v_sub_f32_e32 v64, v64, v84
	v_sub_f32_e32 v81, v81, v84
	v_sub_f32_e32 v65, v65, v84
	v_sub_f32_e32 v82, v82, v84
	v_sub_f32_e32 v66, v66, v84
	v_sub_f32_e32 v83, v83, v84
	v_sub_f32_e32 v67, v67, v84
	v_exp_f32_e32 v68, v68
	v_exp_f32_e32 v164, v112
	v_exp_f32_e32 v69, v69
	v_exp_f32_e32 v165, v113
	v_add_f32_e32 v112, 0, v68
	v_exp_f32_e32 v70, v70
	ds_read_b64_tr_b16 v[52:53], v190 offset:57344
	ds_read_b64_tr_b16 v[54:55], v190 offset:57856
	ds_read_b64_tr_b16 v[84:85], v190 offset:58368
	ds_read_b64_tr_b16 v[86:87], v190 offset:58880
	ds_read_b64_tr_b16 v[88:89], v190 offset:59392
	ds_read_b64_tr_b16 v[90:91], v190 offset:59904
	ds_read_b64_tr_b16 v[92:93], v190 offset:60416
	ds_read_b64_tr_b16 v[94:95], v190 offset:60928
	ds_read_b64_tr_b16 v[96:97], v190 offset:61440
	ds_read_b64_tr_b16 v[98:99], v190 offset:61952
	ds_read_b64_tr_b16 v[100:101], v190 offset:62464
	ds_read_b64_tr_b16 v[102:103], v190 offset:62976
	ds_read_b64_tr_b16 v[104:105], v190 offset:63488
	ds_read_b64_tr_b16 v[106:107], v190 offset:64000
	ds_read_b64_tr_b16 v[108:109], v190 offset:64512
	ds_read_b64_tr_b16 v[110:111], v190 offset:65024
	v_exp_f32_e32 v166, v114
	v_add_f32_e32 v160, 0, v164
	v_add_f32_e32 v112, v112, v69
	v_exp_f32_e32 v71, v71
	v_exp_f32_e32 v167, v115
	v_add_f32_e32 v113, v160, v165
	v_add_f32_e32 v112, v112, v70
	v_exp_f32_e32 v72, v72
	v_add_f32_e32 v113, v113, v166
	v_exp_f32_e32 v56, v56
	v_add_f32_e32 v112, v112, v71
	v_exp_f32_e32 v73, v73
	v_add_f32_e32 v113, v113, v167
	v_exp_f32_e32 v57, v57
	v_add_f32_e32 v112, v112, v72
	v_exp_f32_e32 v74, v74
	v_add_f32_e32 v113, v113, v56
	v_exp_f32_e32 v58, v58
; __device__ __forceinline__ unsigned cvtpk(float lo, float hi) { f32x2 v = {lo, hi}; bf16x2_t b = __builtin_convertvector(v, bf16x2_t); return __builtin_bit_cast(unsigned, b); }
; __device__ __forceinline__ float fadd_s(float a, float b) { float r = a + b; asm volatile("" : "+v"(r)); return r; }
; #define ATT_PACK4(P, B, F) (u32x4){F(P[B], P[B + 1]), F(P[B + 2], P[B + 3]), F(P[B + 4], P[B + 5]), F(P[B + 6], P[B + 7])}
;     bf16x8 kf[8]; kfrags(kf, kslot, r32, hi);
;     f32x16 p0, p1;
; #pragma unroll
;     for (int g = 0; g < 4; ++g) { const f32x4 c0 = ld4(ckt + 8 * g), c1 = ld4(ckt + 32 + 8 * g);
; #pragma unroll
;         for (int i = 0; i < 4; ++i) { p0[4 * g + i] = c0[i]; p1[4 * g + i] = c1[i]; } }
;     u32x4 kn = {0u, 0xBF800000u, 0xBF80BF80u, 0u}; if (hi) { kn.y = 0u; kn.z = 0u; }
;     const bf16x8 kneg = __builtin_bit_cast(bf16x8, kn);
;     p0 = __builtin_amdgcn_mfma_f32_32x32x16_bf16(kneg, st.mq, p0, 0, 0, 0);
;     p1 = __builtin_amdgcn_mfma_f32_32x32x16_bf16(kneg, st.mq, p1, 0, 0, 0);
; #pragma unroll
;     for (int d0 = 0; d0 < 4; ++d0) {
;         p0 = __builtin_amdgcn_mfma_f32_32x32x16_bf16(kf[2 * d0], qr[d0], p0, 0, 0, 0);
;         p1 = __builtin_amdgcn_mfma_f32_32x32x16_bf16(kf[2 * d0 + 1], qr[d0], p1, 0, 0, 0);
;     }
;     ...
;     float sacc = 0.f, sacc2 = 0.f;
; #pragma unroll
;     for (int r = 0; r < 16; ++r) { p0[r] = __builtin_amdgcn_exp2f(p0[r]); p1[r] = __builtin_amdgcn_exp2f(p1[r]); sacc = fadd_s(sacc, p0[r]); sacc2 = fadd_s(sacc2, p1[r]); }
;     st.l = fadd_s(st.l, fadd_s(sacc, sacc2));
;     const u32x4 pw0 = ATT_PACK4(p0, 0, cvtpk), pw1 = ATT_PACK4(p0, 8, cvtpk), pw2 = ATT_PACK4(p1, 0, cvtpk), pw3 = ATT_PACK4(p1, 8, cvtpk);
;     __builtin_amdgcn_sched_barrier(0);
;     ...
;     pv(st.o, vf, pw0, pw1, pw2, pw3);
	v_add_f32_e32 v112, v112, v73
	v_exp_f32_e32 v75, v75
	v_add_f32_e32 v113, v113, v57
	v_exp_f32_e32 v59, v59
	v_add_f32_e32 v112, v112, v74
	v_exp_f32_e32 v76, v76
	v_add_f32_e32 v113, v113, v58
	v_exp_f32_e32 v60, v60
	v_add_f32_e32 v112, v112, v75
	v_exp_f32_e32 v77, v77
	v_add_f32_e32 v113, v113, v59
	v_exp_f32_e32 v61, v61
	v_add_f32_e32 v112, v76, v112
	v_exp_f32_e32 v78, v78
	v_add_f32_e32 v113, v60, v113
	v_exp_f32_e32 v62, v62
	v_add_f32_e32 v112, v77, v112
	v_exp_f32_e32 v79, v79
	v_add_f32_e32 v113, v61, v113
	v_exp_f32_e32 v63, v63
	v_add_f32_e32 v112, v78, v112
	v_exp_f32_e32 v80, v80
	v_add_f32_e32 v113, v62, v113
	v_exp_f32_e32 v64, v64
	v_add_f32_e32 v112, v79, v112
	v_exp_f32_e32 v81, v81
	v_add_f32_e32 v113, v63, v113
	v_exp_f32_e32 v65, v65
	v_add_f32_e32 v112, v80, v112
	v_exp_f32_e32 v82, v82
	v_add_f32_e32 v113, v64, v113
	v_exp_f32_e32 v66, v66
	v_add_f32_e32 v112, v81, v112
	v_exp_f32_e32 v83, v83
	v_add_f32_e32 v113, v65, v113
	v_exp_f32_e32 v67, v67
	v_add_f32_e32 v112, v82, v112
	v_add_f32_e32 v113, v66, v113
	v_add_f32_e32 v112, v83, v112
	v_add_f32_e32 v113, v67, v113
	v_cvt_pk_bf16_f32 v114, v72, v73
	v_add_f32_e32 v112, v112, v113
	v_cvt_pk_bf16_f32 v113, v70, v71
	v_add_f32_e32 v194, v192, v112
	v_cvt_pk_bf16_f32 v112, v68, v69
	v_cvt_pk_bf16_f32 v115, v74, v75
	v_cvt_pk_bf16_f32 v160, v76, v77
	v_cvt_pk_bf16_f32 v161, v78, v79
	v_cvt_pk_bf16_f32 v162, v80, v81
	v_cvt_pk_bf16_f32 v163, v82, v83
	v_cvt_pk_bf16_f32 v164, v164, v165
	v_cvt_pk_bf16_f32 v165, v166, v167
	v_cvt_pk_bf16_f32 v166, v56, v57
	v_cvt_pk_bf16_f32 v167, v58, v59
	v_cvt_pk_bf16_f32 v198, v60, v61
	v_cvt_pk_bf16_f32 v199, v62, v63
	v_cvt_pk_bf16_f32 v200, v64, v65
	v_cvt_pk_bf16_f32 v201, v66, v67
	s_waitcnt lgkmcnt(6)
	v_mfma_f32_32x32x16_bf16 v[68:83], v[112:115], v[52:55], v[20:35]
	v_mfma_f32_32x32x16_bf16 v[52:67], v[112:115], v[96:99], v[36:51]
	v_mfma_f32_32x32x16_bf16 v[68:83], v[160:163], v[84:87], v[68:83]
	s_waitcnt lgkmcnt(4)
	v_mfma_f32_32x32x16_bf16 v[52:67], v[160:163], v[100:103], v[52:67]
	v_mfma_f32_32x32x16_bf16 v[68:83], v[164:167], v[88:91], v[68:83]
	s_waitcnt lgkmcnt(2)
	v_mfma_f32_32x32x16_bf16 v[52:67], v[164:167], v[104:107], v[52:67]
	v_mfma_f32_32x32x16_bf16 v[68:83], v[198:201], v[92:95], v[68:83]
	ds_read_b128 v[84:87], v196
	ds_read_b128 v[88:91], v196 offset:32
	ds_read_b128 v[92:95], v196 offset:64
	ds_read_b128 v[96:99], v196 offset:96
	s_waitcnt lgkmcnt(0)
	v_mfma_f32_32x32x16_bf16 v[52:67], v[198:201], v[108:111], v[52:67]
	ds_read_b128 v[100:103], v196 offset:128
	ds_read_b128 v[104:107], v196 offset:160
	ds_read_b128 v[108:111], v196 offset:192
	ds_read_b128 v[112:115], v196 offset:224
	ds_read_b128 v[160:163], v195
	ds_read_b128 v[164:167], v195 offset:512
	v_mfma_f32_32x32x16_bf16 v[84:99], v[120:123], v[2:5], v[84:99]
	s_waitcnt lgkmcnt(1)
	v_mfma_f32_32x32x16_bf16 v[100:115], v[120:123], v[2:5], v[100:115]
	v_mfma_f32_32x32x16_bf16 v[84:99], v[160:163], v[6:9], v[84:99]
	s_waitcnt lgkmcnt(0)
	v_mfma_f32_32x32x16_bf16 v[100:115], v[164:167], v[6:9], v[100:115]
	ds_read_b128 v[160:163], v195 offset:2048
	ds_read_b128 v[164:167], v195 offset:2560
	s_waitcnt lgkmcnt(0)
	v_mfma_f32_32x32x16_bf16 v[84:99], v[160:163], v[10:13], v[84:99]
	v_mfma_f32_32x32x16_bf16 v[100:115], v[164:167], v[10:13], v[100:115]
	ds_read_b128 v[160:163], v195 offset:4096
	ds_read_b128 v[164:167], v195 offset:4608
	s_waitcnt lgkmcnt(0)
	v_mfma_f32_32x32x16_bf16 v[84:99], v[160:163], v[14:17], v[84:99]
	v_mfma_f32_32x32x16_bf16 v[100:115], v[164:167], v[14:17], v[100:115]
	ds_read_b128 v[160:163], v195 offset:6144
	ds_read_b128 v[164:167], v195 offset:6656
	s_waitcnt lgkmcnt(0)
	v_mfma_f32_32x32x16_bf16 v[84:99], v[160:163], v[116:119], v[84:99]
	v_mfma_f32_32x32x16_bf16 v[100:115], v[164:167], v[116:119], v[100:115]
	s_nop 11
	v_max_f32_e32 v160, v100, v100
	v_max_f32_e32 v161, v84, v84
	v_max_f32_e32 v160, v161, v160
	v_max3_f32 v161, v101, v86, v102
	v_max3_f32 v160, v160, v85, v87
	v_max3_f32 v161, v161, v88, v104
	v_max3_f32 v160, v160, v103, v89
	v_max3_f32 v161, v161, v90, v106
	v_max3_f32 v160, v160, v105, v91
	v_max3_f32 v161, v161, v92, v108
	v_max3_f32 v160, v160, v107, v93
	v_max3_f32 v161, v161, v94, v110
	v_max3_f32 v160, v160, v109, v95
	v_max3_f32 v161, v161, v96, v112
	v_max3_f32 v160, v160, v111, v97
	v_max3_f32 v161, v161, v98, v114
	v_max3_f32 v160, v160, v113, v99
	v_max3_f32 v160, v160, v115, v161
	v_mov_b32_e32 v161, v160
	s_nop 1
	v_permlane32_swap_b32_e32 v160, v161
	v_max_f32_e32 v161, v161, v161
	v_max_f32_e32 v160, v160, v160
	v_max_f32_e32 v160, v160, v161
	s_mov_b32 s3, 0x41000000
	v_cmp_lt_f32_e32 vcc, s3, v160
	s_cbranch_vccz .LBB0_324
; #define LAS __attribute__((address_space(3)))
; #define ATT_LDS_WAIT() asm volatile("s_waitcnt lgkmcnt(0)" ::: "memory")
;     ...
;     if (first || __any(rm > FOX_THR)) {
;         const float dl = first ? rm : fmaxf(rm, 0.f);
;         st.m += dl; st.mq = make_mq(st.m, hi);
; #pragma unroll
;         for (int r = 0; r < 16; ++r) { p0[r] -= dl; p1[r] -= dl; }
;         if (!first) {
;             const float f = __builtin_amdgcn_exp2f(-dl);
;             st.l *= f;
;             if (hi == 0) wsf[r32] = f;
;             ATT_LDS_WAIT();
; #pragma unroll
;             for (int g = 0; g < 4; ++g) { const f32x4 fv = *(const LAS f32x4*)(wsf + 8 * g + 4 * hi);
; #pragma unroll
;                 for (int i = 0; i < 4; ++i) { st.o[0][4 * g + i] *= fv[i]; st.o[1][4 * g + i] *= fv[i]; } }
;         }
	v_max_f32_e32 v160, 0, v160
	v_exp_f32_e64 v161, -v160
	s_and_saveexec_b64 s[4:5], s[6:7]
	ds_write_b32 v182, v161
	s_or_b64 exec, exec, s[4:5]
	v_add_f32_e32 v191, v191, v160
	v_cvt_pk_bf16_f32 v3, v191, 0
	v_lshlrev_b32_e32 v3, 16, v3
	v_sub_f32_e32 v4, v191, v3
	v_cvt_pk_bf16_f32 v162, v4, 0
	v_lshlrev_b32_e32 v162, 16, v162
	v_sub_f32_e32 v4, v4, v162
	s_waitcnt lgkmcnt(0)
	v_add_u32_e32 v197, s78, v172
	v_cvt_pk_bf16_f32 v4, v162, v4
	v_pk_add_f32 v[84:85], v[84:85], v[160:161] op_sel_hi:[1,0] neg_lo:[0,1] neg_hi:[0,1]
	v_pk_add_f32 v[100:101], v[100:101], v[160:161] op_sel_hi:[1,0] neg_lo:[0,1] neg_hi:[0,1]
	v_pk_add_f32 v[86:87], v[86:87], v[160:161] op_sel_hi:[1,0] neg_lo:[0,1] neg_hi:[0,1]
	v_pk_add_f32 v[102:103], v[102:103], v[160:161] op_sel_hi:[1,0] neg_lo:[0,1] neg_hi:[0,1]
	v_pk_add_f32 v[88:89], v[88:89], v[160:161] op_sel_hi:[1,0] neg_lo:[0,1] neg_hi:[0,1]
	v_pk_add_f32 v[104:105], v[104:105], v[160:161] op_sel_hi:[1,0] neg_lo:[0,1] neg_hi:[0,1]
	v_pk_add_f32 v[90:91], v[90:91], v[160:161] op_sel_hi:[1,0] neg_lo:[0,1] neg_hi:[0,1]
	v_pk_add_f32 v[106:107], v[106:107], v[160:161] op_sel_hi:[1,0] neg_lo:[0,1] neg_hi:[0,1]
	v_pk_add_f32 v[92:93], v[92:93], v[160:161] op_sel_hi:[1,0] neg_lo:[0,1] neg_hi:[0,1]
	v_pk_add_f32 v[108:109], v[108:109], v[160:161] op_sel_hi:[1,0] neg_lo:[0,1] neg_hi:[0,1]
	v_pk_add_f32 v[94:95], v[94:95], v[160:161] op_sel_hi:[1,0] neg_lo:[0,1] neg_hi:[0,1]
	v_pk_add_f32 v[110:111], v[110:111], v[160:161] op_sel_hi:[1,0] neg_lo:[0,1] neg_hi:[0,1]
	v_pk_add_f32 v[96:97], v[96:97], v[160:161] op_sel_hi:[1,0] neg_lo:[0,1] neg_hi:[0,1]
	v_pk_add_f32 v[112:113], v[112:113], v[160:161] op_sel_hi:[1,0] neg_lo:[0,1] neg_hi:[0,1]
	v_pk_add_f32 v[98:99], v[98:99], v[160:161] op_sel_hi:[1,0] neg_lo:[0,1] neg_hi:[0,1]
	v_pk_add_f32 v[114:115], v[114:115], v[160:161] op_sel_hi:[1,0] neg_lo:[0,1] neg_hi:[0,1]
	v_mul_f32_e32 v194, v194, v161
	ds_read_b128 v[160:163], v197
	ds_read_b128 v[164:167], v197 offset:32
	ds_read_b128 v[198:201], v197 offset:64
	ds_read_b128 v[202:205], v197 offset:96
	v_cvt_pk_bf16_f32 v3, 1.0, v3
	v_cndmask_b32_e64 v4, 0, v4, s[6:7]
	v_cndmask_b32_e64 v3, 0, v3, s[6:7]
	s_waitcnt lgkmcnt(1)
	v_pk_mul_f32 v[76:77], v[76:77], v[198:199]
	s_waitcnt lgkmcnt(0)
	v_pk_mul_f32 v[80:81], v[80:81], v[202:203]
	v_pk_mul_f32 v[72:73], v[72:73], v[164:165]
	v_pk_mul_f32 v[82:83], v[82:83], v[204:205]
	v_pk_mul_f32 v[78:79], v[78:79], v[200:201]
	v_pk_mul_f32 v[74:75], v[74:75], v[166:167]
	v_pk_mul_f32 v[70:71], v[70:71], v[162:163]
	v_pk_mul_f32 v[68:69], v[68:69], v[160:161]
	v_pk_mul_f32 v[64:65], v[64:65], v[202:203]
	v_pk_mul_f32 v[60:61], v[60:61], v[198:199]
	v_pk_mul_f32 v[56:57], v[56:57], v[164:165]
	v_pk_mul_f32 v[66:67], v[66:67], v[204:205]
	v_pk_mul_f32 v[62:63], v[62:63], v[200:201]
	v_pk_mul_f32 v[58:59], v[58:59], v[166:167]
	v_pk_mul_f32 v[54:55], v[54:55], v[162:163]
	v_pk_mul_f32 v[52:53], v[52:53], v[160:161]

; __device__ __forceinline__ int crow(int r, int hi) { return (r & 3) + 8 * (r >> 2) + 4 * hi; }
; __device__ __forceinline__ float swap_max(float m) { auto rr = __builtin_amdgcn_permlane32_swap(__float_as_uint(m), __float_as_uint(m), false, false); return fmaxf(__uint_as_float(rr[0]), __uint_as_float(rr[1])); }
; __device__ __forceinline__ float max3f(float a, float b, float c) { return __builtin_fmaxf(__builtin_fmaxf(a, b), c); }
;     bf16x8 kf[8]; kfrags(kf, kslot, r32, hi);
;     f32x16 p0, p1;
; #pragma unroll
;     for (int g = 0; g < 4; ++g) { const f32x4 c0 = ld4(ckt + 8 * g), c1 = ld4(ckt + 32 + 8 * g);
; #pragma unroll
;         for (int i = 0; i < 4; ++i) { p0[4 * g + i] = c0[i]; p1[4 * g + i] = c1[i]; } }
;     u32x4 kn = {0u, 0xBF800000u, 0xBF80BF80u, 0u}; if (hi) { kn.y = 0u; kn.z = 0u; }
;     const bf16x8 kneg = __builtin_bit_cast(bf16x8, kn);
;     p0 = __builtin_amdgcn_mfma_f32_32x32x16_bf16(kneg, st.mq, p0, 0, 0, 0);
;     p1 = __builtin_amdgcn_mfma_f32_32x32x16_bf16(kneg, st.mq, p1, 0, 0, 0);
; #pragma unroll
;     for (int d0 = 0; d0 < 4; ++d0) {
;         p0 = __builtin_amdgcn_mfma_f32_32x32x16_bf16(kf[2 * d0], qr[d0], p0, 0, 0, 0);
;         p1 = __builtin_amdgcn_mfma_f32_32x32x16_bf16(kf[2 * d0 + 1], qr[d0], p1, 0, 0, 0);
;     }
;     __builtin_amdgcn_sched_barrier(0);
;     if (LEVEL == 2) { asm volatile("" :: "v"(p0), "v"(p1)); return; }
;     if (masked) {
;         asm volatile("; masked tile" ::: "memory");
; #pragma unroll
;         for (int r = 0; r < 16; ++r) { const int kv = crow(r, hi); if (kv >= qlim) p0[r] = NEG; if (kv + 32 >= qlim) p1[r] = NEG; }
;     }
;     float rm = max3f(p0[0], p1[0], p0[1]), rm2 = max3f(p1[1], p0[2], p1[2]);
; #pragma unroll
;     for (int r = 3; r < 15; r += 2) { rm = max3f(rm, p0[r], p1[r]); rm2 = max3f(rm2, p0[r + 1], p1[r + 1]); }
;     rm = max3f(rm, p0[15], p1[15]); rm = swap_max(max3f(rm, rm2, rm2));
;     if (first || __any(rm > FOX_THR)) {
;         const float dl = first ? rm : fmaxf(rm, 0.f);
;         st.m += dl; st.mq = make_mq(st.m, hi);
; #pragma unroll
;         for (int r = 0; r < 16; ++r) { p0[r] -= dl; p1[r] -= dl; }
.LBB0_325:
	s_and_b64 vcc, exec, s[4:5]
	s_cbranch_vccz .LBB0_327
	s_nop 7
	ds_read_b128 v[68:71], v196
	ds_read_b128 v[72:75], v196 offset:32
	ds_read_b128 v[76:79], v196 offset:64
	ds_read_b128 v[80:83], v196 offset:96
	ds_read_b128 v[52:55], v196 offset:128
	ds_read_b128 v[56:59], v196 offset:160
	ds_read_b128 v[60:63], v196 offset:192
	ds_read_b128 v[64:67], v196 offset:224
	ds_read_b128 v[84:87], v195
	s_waitcnt lgkmcnt(5)
	v_mfma_f32_32x32x16_bf16 v[68:83], v[120:123], v[156:159], v[68:83]
	s_waitcnt lgkmcnt(0)
	v_mfma_f32_32x32x16_bf16 v[68:83], v[84:87], v[6:9], v[68:83]
	ds_read_b128 v[84:87], v195 offset:512
	v_mfma_f32_32x32x16_bf16 v[52:67], v[120:123], v[156:159], v[52:67]
	s_waitcnt lgkmcnt(0)
	v_mfma_f32_32x32x16_bf16 v[52:67], v[84:87], v[6:9], v[52:67]
	ds_read_b128 v[84:87], v195 offset:2048
	s_waitcnt lgkmcnt(0)
	v_mfma_f32_32x32x16_bf16 v[68:83], v[84:87], v[10:13], v[68:83]
	ds_read_b128 v[84:87], v195 offset:2560
	s_waitcnt lgkmcnt(0)
	v_mfma_f32_32x32x16_bf16 v[52:67], v[84:87], v[10:13], v[52:67]
	ds_read_b128 v[84:87], v195 offset:4096
	s_waitcnt lgkmcnt(0)
	v_mfma_f32_32x32x16_bf16 v[68:83], v[84:87], v[14:17], v[68:83]
	ds_read_b128 v[84:87], v195 offset:4608
	s_waitcnt lgkmcnt(0)
	v_mfma_f32_32x32x16_bf16 v[52:67], v[84:87], v[14:17], v[52:67]
	ds_read_b128 v[84:87], v195 offset:6144
	s_waitcnt lgkmcnt(0)
	v_mfma_f32_32x32x16_bf16 v[68:83], v[84:87], v[116:119], v[68:83]
	ds_read_b128 v[84:87], v195 offset:6656
	s_waitcnt lgkmcnt(0)
	v_mfma_f32_32x32x16_bf16 v[52:67], v[84:87], v[116:119], v[52:67]
	s_and_b64 vcc, s[70:71], s[66:67]
	s_nop 7
	v_cndmask_b32_e32 v82, v82, v18, vcc
	s_and_b64 vcc, vcc, s[62:63]
	v_cndmask_b32_e32 v81, v81, v18, vcc
	s_and_b64 vcc, vcc, s[58:59]
	v_cndmask_b32_e32 v80, v80, v18, vcc
	s_and_b64 vcc, vcc, s[54:55]
	v_cndmask_b32_e32 v79, v79, v18, vcc
	s_and_b64 vcc, vcc, s[50:51]
	v_cndmask_b32_e32 v78, v78, v18, vcc
	s_and_b64 vcc, vcc, s[46:47]
	v_cndmask_b32_e32 v77, v77, v18, vcc
	s_and_b64 vcc, vcc, s[42:43]
	v_cndmask_b32_e32 v76, v76, v18, vcc
	s_and_b64 vcc, vcc, s[38:39]
	v_cndmask_b32_e32 v75, v75, v18, vcc
	s_and_b64 vcc, vcc, s[34:35]
	v_cndmask_b32_e32 v74, v74, v18, vcc
	s_and_b64 vcc, vcc, s[28:29]
	v_cndmask_b32_e32 v73, v73, v18, vcc
	s_and_b64 vcc, vcc, s[24:25]
	v_cndmask_b32_e64 v3, v68, v18, s[8:9]
	v_cndmask_b32_e32 v72, v72, v18, vcc
	s_and_b64 vcc, vcc, s[20:21]
	v_cndmask_b32_e64 v3, v3, v68, s[12:13]
	v_cndmask_b32_e64 v4, v18, v69, s[12:13]
	v_cndmask_b32_e32 v71, v71, v18, vcc
	s_and_b64 vcc, vcc, s[16:17]
	v_cndmask_b32_e32 v69, v69, v4, vcc
	v_cndmask_b32_e32 v68, v68, v3, vcc
	v_cndmask_b32_e32 v70, v70, v18, vcc
	s_and_b64 vcc, s[72:73], s[68:69]
	v_cndmask_b32_e32 v66, v66, v18, vcc
	s_and_b64 vcc, vcc, s[64:65]
	v_cndmask_b32_e32 v65, v65, v18, vcc
	s_and_b64 vcc, vcc, s[60:61]
	v_cndmask_b32_e32 v64, v64, v18, vcc
	s_and_b64 vcc, vcc, s[56:57]
	v_cndmask_b32_e32 v63, v63, v18, vcc
	s_and_b64 vcc, vcc, s[52:53]
	v_cndmask_b32_e32 v62, v62, v18, vcc
	s_and_b64 vcc, vcc, s[48:49]
	v_cndmask_b32_e32 v61, v61, v18, vcc
	s_and_b64 vcc, vcc, s[44:45]
	v_cndmask_b32_e32 v60, v60, v18, vcc
	s_and_b64 vcc, vcc, s[40:41]
	v_cndmask_b32_e32 v59, v59, v18, vcc
	s_and_b64 vcc, vcc, s[36:37]
	v_cndmask_b32_e32 v58, v58, v18, vcc
	s_and_b64 vcc, vcc, s[30:31]
	v_cndmask_b32_e32 v57, v57, v18, vcc
	s_and_b64 vcc, vcc, s[26:27]
	v_cndmask_b32_e32 v56, v56, v18, vcc
	s_and_b64 vcc, vcc, s[22:23]
	v_cndmask_b32_e32 v55, v55, v18, vcc
	s_and_b64 vcc, vcc, s[18:19]
	v_cndmask_b32_e32 v54, v54, v18, vcc
	s_and_b64 vcc, vcc, s[14:15]
	v_cndmask_b32_e32 v53, v53, v18, vcc
	s_and_b64 vcc, vcc, s[10:11]
	v_cndmask_b32_e32 v52, v52, v18, vcc
	v_max_f32_e32 v3, v68, v68
	v_max_f32_e32 v4, v52, v52
	v_max_f32_e32 v3, v3, v4
	v_max3_f32 v4, v53, v70, v54
	v_max3_f32 v3, v3, v69, v71
	v_max3_f32 v4, v4, v72, v56
	v_max3_f32 v3, v3, v55, v73
	v_max3_f32 v4, v4, v74, v58
	v_max3_f32 v3, v3, v57, v75
	v_max3_f32 v4, v4, v76, v60
	v_max3_f32 v3, v3, v59, v77
	v_max3_f32 v4, v4, v78, v62
	v_max3_f32 v3, v3, v61, v79
	v_cndmask_b32_e64 v83, v83, v18, s[70:71]
	v_max3_f32 v4, v4, v80, v64
	v_max3_f32 v3, v3, v63, v81
	v_cndmask_b32_e64 v67, v67, v18, s[72:73]
	v_max3_f32 v4, v4, v82, v66
	v_max3_f32 v3, v3, v65, v83
	v_max3_f32 v3, v3, v67, v4
	v_mov_b32_e32 v4, v3
	s_nop 1
	v_permlane32_swap_b32_e32 v3, v4
	v_max_f32_e32 v4, v4, v4
	v_max_f32_e32 v3, v3, v3
	v_max_f32_e32 v84, v3, v4
	v_add_f32_e32 v191, v193, v84
	v_cvt_pk_bf16_f32 v3, v191, 0
	v_lshlrev_b32_e32 v3, 16, v3
	v_sub_f32_e32 v4, v191, v3
	v_cvt_pk_bf16_f32 v85, v4, 0
	v_lshlrev_b32_e32 v85, 16, v85
	v_sub_f32_e32 v4, v4, v85
	v_cvt_pk_bf16_f32 v3, 1.0, v3
	v_cvt_pk_bf16_f32 v4, v85, v4
	v_sub_f32_e32 v68, v68, v84
	v_sub_f32_e32 v69, v69, v84
	v_sub_f32_e32 v70, v70, v84
; #define LAS __attribute__((address_space(3)))
; __device__ __forceinline__ unsigned cvtpk(float lo, float hi) { f32x2 v = {lo, hi}; bf16x2_t b = __builtin_convertvector(v, bf16x2_t); return __builtin_bit_cast(unsigned, b); }
; __device__ __forceinline__ float fadd_s(float a, float b) { float r = a + b; asm volatile("" : "+v"(r)); return r; }
; #define ATT_LDS_WAIT() asm volatile("s_waitcnt lgkmcnt(0)" ::: "memory")
; #define ATT_PACK4(P, B, F) (u32x4){F(P[B], P[B + 1]), F(P[B + 2], P[B + 3]), F(P[B + 4], P[B + 5]), F(P[B + 6], P[B + 7])}
;     ...
;         for (int r = 0; r < 16; ++r) { p0[r] -= dl; p1[r] -= dl; }
;         if (!first) {
;             const float f = __builtin_amdgcn_exp2f(-dl);
;             st.l *= f;
;             if (hi == 0) wsf[r32] = f;
;             ATT_LDS_WAIT();
; #pragma unroll
;             for (int g = 0; g < 4; ++g) { const f32x4 fv = *(const LAS f32x4*)(wsf + 8 * g + 4 * hi);
; #pragma unroll
;                 for (int i = 0; i < 4; ++i) { st.o[0][4 * g + i] *= fv[i]; st.o[1][4 * g + i] *= fv[i]; } }
;         }
;     }
;     __builtin_amdgcn_sched_barrier(0);
;     VFrags vf; vfrags(vf, vp);
;     float sacc = 0.f, sacc2 = 0.f;
; #pragma unroll
;     for (int r = 0; r < 16; ++r) { p0[r] = __builtin_amdgcn_exp2f(p0[r]); p1[r] = __builtin_amdgcn_exp2f(p1[r]); sacc = fadd_s(sacc, p0[r]); sacc2 = fadd_s(sacc2, p1[r]); }
;     st.l = fadd_s(st.l, fadd_s(sacc, sacc2));
;     const u32x4 pw0 = ATT_PACK4(p0, 0, cvtpk), pw1 = ATT_PACK4(p0, 8, cvtpk), pw2 = ATT_PACK4(p1, 0, cvtpk), pw3 = ATT_PACK4(p1, 8, cvtpk);
;     __builtin_amdgcn_sched_barrier(0);
;     ...
;     pv(st.o, vf, pw0, pw1, pw2, pw3);
	v_sub_f32_e32 v71, v71, v84
	v_sub_f32_e32 v72, v72, v84
	v_sub_f32_e32 v56, v56, v84
	v_sub_f32_e32 v73, v73, v84
	v_sub_f32_e32 v57, v57, v84
	v_sub_f32_e32 v74, v74, v84
	v_sub_f32_e32 v58, v58, v84
	v_sub_f32_e32 v75, v75, v84
	v_sub_f32_e32 v59, v59, v84
	v_sub_f32_e32 v76, v76, v84
	v_sub_f32_e32 v60, v60, v84
	v_sub_f32_e32 v77, v77, v84
	v_sub_f32_e32 v61, v61, v84
	v_sub_f32_e32 v78, v78, v84
	v_sub_f32_e32 v62, v62, v84
	v_sub_f32_e32 v79, v79, v84
	v_sub_f32_e32 v63, v63, v84
	v_sub_f32_e32 v80, v80, v84
	v_sub_f32_e32 v64, v64, v84
	v_sub_f32_e32 v81, v81, v84
	v_sub_f32_e32 v65, v65, v84
	v_sub_f32_e32 v82, v82, v84
	v_sub_f32_e32 v66, v66, v84
	v_sub_f32_e32 v83, v83, v84
	v_sub_f32_e32 v67, v67, v84
	v_cndmask_b32_e64 v4, 0, v4, s[6:7]
	v_cndmask_b32_e64 v3, 0, v3, s[6:7]
	v_sub_f32_e32 v112, v52, v84
	v_sub_f32_e32 v113, v53, v84
	v_sub_f32_e32 v114, v54, v84
	v_sub_f32_e32 v115, v55, v84
	v_exp_f32_e32 v68, v68
	v_exp_f32_e32 v164, v112
	v_exp_f32_e32 v69, v69
	v_exp_f32_e32 v165, v113
	v_add_f32_e32 v112, 0, v68
	v_exp_f32_e32 v70, v70
	ds_read_b64_tr_b16 v[52:53], v190 offset:49152
	ds_read_b64_tr_b16 v[54:55], v190 offset:49664
	ds_read_b64_tr_b16 v[84:85], v190 offset:50176
	ds_read_b64_tr_b16 v[86:87], v190 offset:50688
	ds_read_b64_tr_b16 v[88:89], v190 offset:51200
	ds_read_b64_tr_b16 v[90:91], v190 offset:51712
	ds_read_b64_tr_b16 v[92:93], v190 offset:52224
	ds_read_b64_tr_b16 v[94:95], v190 offset:52736
	ds_read_b64_tr_b16 v[96:97], v190 offset:53248
	ds_read_b64_tr_b16 v[98:99], v190 offset:53760
	ds_read_b64_tr_b16 v[100:101], v190 offset:54272
	ds_read_b64_tr_b16 v[102:103], v190 offset:54784
	ds_read_b64_tr_b16 v[104:105], v190 offset:55296
	ds_read_b64_tr_b16 v[106:107], v190 offset:55808
	ds_read_b64_tr_b16 v[108:109], v190 offset:56320
	ds_read_b64_tr_b16 v[110:111], v190 offset:56832
	v_exp_f32_e32 v166, v114
	v_add_f32_e32 v160, 0, v164
	v_add_f32_e32 v112, v112, v69
	v_exp_f32_e32 v71, v71
	v_exp_f32_e32 v167, v115
	v_add_f32_e32 v113, v160, v165
	v_add_f32_e32 v112, v112, v70
	v_exp_f32_e32 v72, v72
	v_add_f32_e32 v113, v113, v166
	v_exp_f32_e32 v56, v56
	v_add_f32_e32 v112, v112, v71
	v_exp_f32_e32 v73, v73
	v_add_f32_e32 v113, v113, v167
	v_exp_f32_e32 v57, v57
	v_add_f32_e32 v112, v112, v72
	v_exp_f32_e32 v74, v74
	v_add_f32_e32 v113, v113, v56
	v_exp_f32_e32 v58, v58
	v_add_f32_e32 v112, v112, v73
	v_exp_f32_e32 v75, v75
	v_add_f32_e32 v113, v113, v57
	v_exp_f32_e32 v59, v59
	v_add_f32_e32 v112, v112, v74
	v_exp_f32_e32 v76, v76
	v_add_f32_e32 v113, v113, v58
	v_exp_f32_e32 v60, v60
	v_add_f32_e32 v112, v112, v75
	v_exp_f32_e32 v77, v77
	v_add_f32_e32 v113, v113, v59
	v_exp_f32_e32 v61, v61
	v_add_f32_e32 v112, v76, v112
	v_exp_f32_e32 v78, v78
	v_add_f32_e32 v113, v60, v113
	v_exp_f32_e32 v62, v62
	v_add_f32_e32 v112, v77, v112
	v_exp_f32_e32 v79, v79
	v_add_f32_e32 v113, v61, v113
	v_exp_f32_e32 v63, v63
	v_add_f32_e32 v112, v78, v112
	v_exp_f32_e32 v80, v80
	v_add_f32_e32 v113, v62, v113
	v_exp_f32_e32 v64, v64
	v_add_f32_e32 v112, v79, v112
	v_exp_f32_e32 v81, v81
	v_add_f32_e32 v113, v63, v113
	v_exp_f32_e32 v65, v65
	v_add_f32_e32 v112, v80, v112
	v_exp_f32_e32 v82, v82
	v_add_f32_e32 v113, v64, v113
	v_exp_f32_e32 v66, v66
	v_add_f32_e32 v112, v81, v112
	v_exp_f32_e32 v83, v83
	v_add_f32_e32 v113, v65, v113
	v_exp_f32_e32 v67, v67
	v_add_f32_e32 v112, v82, v112
	v_add_f32_e32 v113, v66, v113
	v_add_f32_e32 v112, v83, v112
	v_add_f32_e32 v113, v67, v113
	v_cvt_pk_bf16_f32 v160, v76, v77
	v_add_f32_e32 v112, v112, v113
	v_cvt_pk_bf16_f32 v161, v78, v79
	v_add_f32_e32 v194, v192, v112
	v_cvt_pk_bf16_f32 v162, v80, v81
	v_cvt_pk_bf16_f32 v163, v82, v83
	v_cvt_pk_bf16_f32 v112, v68, v69
	v_cvt_pk_bf16_f32 v113, v70, v71
	v_cvt_pk_bf16_f32 v114, v72, v73
	v_cvt_pk_bf16_f32 v115, v74, v75
	v_cvt_pk_bf16_f32 v164, v164, v165
	v_cvt_pk_bf16_f32 v165, v166, v167
	v_cvt_pk_bf16_f32 v166, v56, v57
	v_cvt_pk_bf16_f32 v167, v58, v59
	v_cvt_pk_bf16_f32 v196, v60, v61
	v_cvt_pk_bf16_f32 v197, v62, v63
	v_cvt_pk_bf16_f32 v198, v64, v65
	v_cvt_pk_bf16_f32 v199, v66, v67
	s_waitcnt lgkmcnt(6)
	v_mfma_f32_32x32x16_bf16 v[68:83], v[112:115], v[52:55], v[20:35]
	v_mfma_f32_32x32x16_bf16 v[52:67], v[112:115], v[96:99], v[36:51]
	v_mfma_f32_32x32x16_bf16 v[68:83], v[160:163], v[84:87], v[68:83]
	s_waitcnt lgkmcnt(4)
	v_mfma_f32_32x32x16_bf16 v[52:67], v[160:163], v[100:103], v[52:67]
	v_mov_b64_e32 v[162:163], v[4:5]
	v_mov_b64_e32 v[160:161], v[2:3]
	v_mfma_f32_32x32x16_bf16 v[68:83], v[164:167], v[88:91], v[68:83]
	s_waitcnt lgkmcnt(2)
	v_mfma_f32_32x32x16_bf16 v[52:67], v[164:167], v[104:107], v[52:67]
	v_mfma_f32_32x32x16_bf16 v[68:83], v[196:199], v[92:95], v[68:83]
	s_waitcnt lgkmcnt(0)
	v_mfma_f32_32x32x16_bf16 v[52:67], v[196:199], v[108:111], v[52:67]

; __device__ __forceinline__ bool fox_pair_qs(FoxState& st, PairP& pp, lds_cptr kslotB, const bf16x8 (&qr)[4], const LAS u32x2* augB  , bool careful, int r32, int hi, LAS float* wsf) {
;     bf16x8 kfA[8], kfB[8]; kfrags(kfA, kslotB + 8192, r32, hi); kfrags(kfB, kslotB, r32, hi);
;     const u32x2 t0 = augB[64], t1 = augB[96], t2 = augB[0], t3 = augB[32];
;     const f32x16 zz = {};
;     f32x16 a0, a1, b0, b1;
;     a0 = __builtin_amdgcn_mfma_f32_32x32x16_bf16(__builtin_bit_cast(bf16x8, (u32x4){t0.x, t0.y, 0xBF80BF80u, 0u}), st.mq, zz, 0, 0, 0);
;     a1 = __builtin_amdgcn_mfma_f32_32x32x16_bf16(__builtin_bit_cast(bf16x8, (u32x4){t1.x, t1.y, 0xBF80BF80u, 0u}), st.mq, zz, 0, 0, 0);
;     b0 = __builtin_amdgcn_mfma_f32_32x32x16_bf16(__builtin_bit_cast(bf16x8, (u32x4){t2.x, t2.y, 0xBF80BF80u, 0u}), st.mq, zz, 0, 0, 0);
;     b1 = __builtin_amdgcn_mfma_f32_32x32x16_bf16(__builtin_bit_cast(bf16x8, (u32x4){t3.x, t3.y, 0xBF80BF80u, 0u}), st.mq, zz, 0, 0, 0);
; #pragma unroll
;     for (int d0 = 0; d0 < 4; ++d0) {
;         a0 = __builtin_amdgcn_mfma_f32_32x32x16_bf16(kfA[2 * d0], qr[d0], a0, 0, 0, 0); a1 = __builtin_amdgcn_mfma_f32_32x32x16_bf16(kfA[2 * d0 + 1], qr[d0], a1, 0, 0, 0);
;         b0 = __builtin_amdgcn_mfma_f32_32x32x16_bf16(kfB[2 * d0], qr[d0], b0, 0, 0, 0); b1 = __builtin_amdgcn_mfma_f32_32x32x16_bf16(kfB[2 * d0 + 1], qr[d0], b1, 0, 0, 0);
;     }
.LBB0_330:
	ds_read_b64 v[56:57], v124 offset:512
	ds_read_b64 v[60:61], v124 offset:768
	ds_read_b64 v[52:53], v124
	ds_read_b64 v[70:71], v124 offset:256
	ds_read_b128 v[196:199], v125 offset:8192
	ds_read_b128 v[200:203], v125 offset:8704
	ds_read_b128 v[204:207], v125
	ds_read_b128 v[208:211], v125 offset:512
	ds_read_b128 v[220:223], v125 offset:10240
	ds_read_b128 v[224:227], v125 offset:10752
	ds_read_b128 v[228:231], v125 offset:2048
	ds_read_b128 v[232:235], v125 offset:2560
	v_mov_b64_e32 v[58:59], s[86:87]
	v_mov_b64_e32 v[62:63], s[86:87]
	v_mov_b64_e32 v[54:55], s[86:87]
	v_mov_b64_e32 v[72:73], s[86:87]
	s_xor_b64 s[4:5], s[82:83], -1
	s_and_b64 vcc, exec, s[4:5]
	s_waitcnt lgkmcnt(10)
	v_mfma_f32_32x32x16_bf16 v[84:99], v[56:59], v[160:163], 0
	v_mfma_f32_32x32x16_bf16 v[100:115], v[60:63], v[160:163], 0
	s_waitcnt lgkmcnt(8)
	v_mfma_f32_32x32x16_bf16 v[52:67], v[52:55], v[160:163], 0
	v_mfma_f32_32x32x16_bf16 v[68:83], v[70:73], v[160:163], 0
	s_waitcnt lgkmcnt(6)
	v_mfma_f32_32x32x16_bf16 v[84:99], v[196:199], v[6:9], v[84:99]
	ds_read_b128 v[196:199], v125 offset:12288
	v_mfma_f32_32x32x16_bf16 v[100:115], v[200:203], v[6:9], v[100:115]
	ds_read_b128 v[200:203], v125 offset:12800
	s_waitcnt lgkmcnt(6)
	v_mfma_f32_32x32x16_bf16 v[52:67], v[204:207], v[6:9], v[52:67]
	ds_read_b128 v[204:207], v125 offset:4096
	v_mfma_f32_32x32x16_bf16 v[68:83], v[208:211], v[6:9], v[68:83]
	ds_read_b128 v[208:211], v125 offset:4608
	s_waitcnt lgkmcnt(6)
	v_mfma_f32_32x32x16_bf16 v[84:99], v[220:223], v[10:13], v[84:99]
	ds_read_b128 v[220:223], v125 offset:14336
	v_mfma_f32_32x32x16_bf16 v[100:115], v[224:227], v[10:13], v[100:115]
	ds_read_b128 v[224:227], v125 offset:14848
	s_waitcnt lgkmcnt(6)
	v_mfma_f32_32x32x16_bf16 v[52:67], v[228:231], v[10:13], v[52:67]
	ds_read_b128 v[228:231], v125 offset:6144
	v_mfma_f32_32x32x16_bf16 v[68:83], v[232:235], v[10:13], v[68:83]
	ds_read_b128 v[232:235], v125 offset:6656
	s_waitcnt lgkmcnt(6)
	v_mfma_f32_32x32x16_bf16 v[84:99], v[196:199], v[14:17], v[84:99]
	v_mfma_f32_32x32x16_bf16 v[100:115], v[200:203], v[14:17], v[100:115]
	s_waitcnt lgkmcnt(4)
	v_mfma_f32_32x32x16_bf16 v[52:67], v[204:207], v[14:17], v[52:67]
	v_mfma_f32_32x32x16_bf16 v[68:83], v[208:211], v[14:17], v[68:83]
	s_waitcnt lgkmcnt(2)
	v_mfma_f32_32x32x16_bf16 v[84:99], v[220:223], v[116:119], v[84:99]
	v_mfma_f32_32x32x16_bf16 v[100:115], v[224:227], v[116:119], v[100:115]
	s_waitcnt lgkmcnt(0)
	v_mfma_f32_32x32x16_bf16 v[52:67], v[228:231], v[116:119], v[52:67]
	v_mfma_f32_32x32x16_bf16 v[68:83], v[232:235], v[116:119], v[68:83]
	s_nop 2
	s_cbranch_vccnz .LBB0_334
; #define LAS __attribute__((address_space(3)))
; __device__ __forceinline__ float swap_max(float m) { auto rr = __builtin_amdgcn_permlane32_swap(__float_as_uint(m), __float_as_uint(m), false, false); return fmaxf(__uint_as_float(rr[0]), __uint_as_float(rr[1])); }
; __device__ __forceinline__ float max3f(float a, float b, float c) { return __builtin_fmaxf(__builtin_fmaxf(a, b), c); }
; #define ATT_LDS_WAIT() asm volatile("s_waitcnt lgkmcnt(0)" ::: "memory")
; __device__ __forceinline__ bool fox_pair_qs(FoxState& st, PairP& pp, lds_cptr kslotB, const bf16x8 (&qr)[4], const LAS u32x2* augB  , bool careful, int r32, int hi, LAS float* wsf) {
;     ...
;     if (careful) {
;         asm volatile("; careful pass: move the reference" ::: "memory");
;         float rm = max3f(a0[0], a1[0], b0[0]), rm2 = max3f(b1[0], a0[1], a1[1]);
;         rm = max3f(rm, b0[1], b1[1]);
; #pragma unroll
;         for (int r = 2; r < 16; ++r) { rm = max3f(rm, a0[r], a1[r]); rm2 = max3f(rm2, b0[r], b1[r]); }
;         rm = swap_max(max3f(rm, rm2, rm2));
;         const float dl = fmaxf(rm, 0.f);
;         st.m += dl; st.mq = make_mq(st.m, hi);
; #pragma unroll
;         for (int r = 0; r < 16; ++r) { a0[r] -= dl; a1[r] -= dl; b0[r] -= dl; b1[r] -= dl; }
;         const float f = __builtin_amdgcn_exp2f(-dl);
;         st.l *= f;
;         if (hi == 0) wsf[r32] = f;
;         ATT_LDS_WAIT();
; #pragma unroll
;         for (int g = 0; g < 4; ++g) { const f32x4 fv = *(const LAS f32x4*)(wsf + 8 * g + 4 * hi);
; #pragma unroll
;             for (int i = 0; i < 4; ++i) { st.o[0][4 * g + i] *= fv[i]; st.o[1][4 * g + i] *= fv[i]; } }
;     }
	s_nop 4
	v_max_f32_e32 v3, v100, v100
	v_max_f32_e32 v4, v84, v84
	v_max_f32_e32 v3, v4, v3
	s_nop 2
	v_max3_f32 v4, v68, v85, v101
	v_max3_f32 v3, v3, v52, v53
	v_max3_f32 v3, v3, v69, v86
	v_max3_f32 v4, v4, v54, v70
	v_max3_f32 v3, v3, v102, v87
	v_max3_f32 v4, v4, v55, v71
	v_max3_f32 v3, v3, v103, v88
	v_max3_f32 v4, v4, v56, v72
	v_max3_f32 v3, v3, v104, v89
	v_max3_f32 v4, v4, v57, v73
	v_max3_f32 v3, v3, v105, v90
	v_max3_f32 v4, v4, v58, v74
	v_max3_f32 v3, v3, v106, v91
	v_max3_f32 v4, v4, v59, v75
	v_max3_f32 v3, v3, v107, v92
	v_max3_f32 v4, v4, v60, v76
	v_max3_f32 v3, v3, v108, v93
	v_max3_f32 v4, v4, v61, v77
	v_max3_f32 v3, v3, v109, v94
	v_max3_f32 v4, v4, v62, v78
	v_max3_f32 v3, v3, v110, v95
	v_max3_f32 v4, v4, v63, v79
	v_max3_f32 v3, v3, v111, v96
	v_max3_f32 v4, v4, v64, v80
	v_max3_f32 v3, v3, v112, v97
	v_max3_f32 v4, v4, v65, v81
	v_max3_f32 v3, v3, v113, v98
	v_max3_f32 v4, v4, v66, v82
	v_max3_f32 v3, v3, v114, v99
	v_max3_f32 v4, v4, v67, v83
	v_max3_f32 v3, v3, v115, v4
	v_mov_b32_e32 v4, v3
	s_nop 1
	v_permlane32_swap_b32_e32 v3, v4
	v_max3_f32 v126, v3, v4, 0
	v_exp_f32_e64 v127, -v126
	s_and_saveexec_b64 vcc, s[6:7]
	ds_write_b32 v182, v127
	s_or_b64 exec, exec, vcc
	v_add_f32_e32 v191, v191, v126
	v_cvt_pk_bf16_f32 v3, v191, 0
	v_lshlrev_b32_e32 v3, 16, v3
	v_sub_f32_e32 v4, v191, v3
	v_cvt_pk_bf16_f32 v128, v4, 0
	v_lshlrev_b32_e32 v128, 16, v128
	v_sub_f32_e32 v4, v4, v128
	s_waitcnt lgkmcnt(0)
	v_add_u32_e32 v138, s78, v172
	v_cvt_pk_bf16_f32 v4, v128, v4
	v_sub_f32_e32 v99, v99, v126
	v_sub_f32_e32 v98, v98, v126
	v_sub_f32_e32 v97, v97, v126
	v_sub_f32_e32 v96, v96, v126
	v_sub_f32_e32 v95, v95, v126
	v_sub_f32_e32 v94, v94, v126
	v_sub_f32_e32 v93, v93, v126
	v_sub_f32_e32 v92, v92, v126
	v_sub_f32_e32 v91, v91, v126
	v_sub_f32_e32 v90, v90, v126
	v_sub_f32_e32 v89, v89, v126
	v_sub_f32_e32 v88, v88, v126
	v_sub_f32_e32 v87, v87, v126
	v_sub_f32_e32 v86, v86, v126
	v_sub_f32_e32 v85, v85, v126
	v_sub_f32_e32 v84, v84, v126
	v_sub_f32_e32 v115, v115, v126
	v_sub_f32_e32 v114, v114, v126
	v_sub_f32_e32 v113, v113, v126
	v_sub_f32_e32 v112, v112, v126
	v_sub_f32_e32 v111, v111, v126
	v_sub_f32_e32 v110, v110, v126
	v_sub_f32_e32 v109, v109, v126
	v_sub_f32_e32 v108, v108, v126
	v_sub_f32_e32 v107, v107, v126
	v_sub_f32_e32 v106, v106, v126
	v_sub_f32_e32 v105, v105, v126
	v_sub_f32_e32 v104, v104, v126
	v_sub_f32_e32 v103, v103, v126
	v_sub_f32_e32 v102, v102, v126
	v_sub_f32_e32 v101, v101, v126
	v_sub_f32_e32 v100, v100, v126
	v_sub_f32_e32 v67, v67, v126
	v_sub_f32_e32 v66, v66, v126
	v_sub_f32_e32 v65, v65, v126
	v_sub_f32_e32 v64, v64, v126
	v_sub_f32_e32 v63, v63, v126
	v_sub_f32_e32 v62, v62, v126
	v_sub_f32_e32 v61, v61, v126
	v_sub_f32_e32 v60, v60, v126
	v_sub_f32_e32 v59, v59, v126
	v_sub_f32_e32 v58, v58, v126
	v_sub_f32_e32 v57, v57, v126
	v_sub_f32_e32 v56, v56, v126
	v_sub_f32_e32 v55, v55, v126
	v_sub_f32_e32 v54, v54, v126
	v_sub_f32_e32 v53, v53, v126
	v_sub_f32_e32 v52, v52, v126
	v_sub_f32_e32 v83, v83, v126
	v_sub_f32_e32 v82, v82, v126
	v_sub_f32_e32 v81, v81, v126
	v_sub_f32_e32 v80, v80, v126
	v_sub_f32_e32 v79, v79, v126
	v_sub_f32_e32 v78, v78, v126
	v_sub_f32_e32 v77, v77, v126
	v_sub_f32_e32 v76, v76, v126
	v_sub_f32_e32 v75, v75, v126
	v_sub_f32_e32 v74, v74, v126
	v_sub_f32_e32 v73, v73, v126
	v_sub_f32_e32 v72, v72, v126
	v_sub_f32_e32 v71, v71, v126
	v_sub_f32_e32 v70, v70, v126
	v_sub_f32_e32 v69, v69, v126
	v_sub_f32_e32 v68, v68, v126
	v_mul_f32_e32 v194, v194, v127
	ds_read_b128 v[126:129], v138
	ds_read_b128 v[130:133], v138 offset:32
	ds_read_b128 v[134:137], v138 offset:64
	ds_read_b128 v[138:141], v138 offset:96
	v_cvt_pk_bf16_f32 v3, 1.0, v3
	v_cndmask_b32_e64 v4, 0, v4, s[6:7]
	v_cndmask_b32_e64 v3, 0, v3, s[6:7]
	v_mov_b64_e32 v[162:163], v[4:5]
	s_waitcnt lgkmcnt(0)
	v_pk_mul_f32 v[32:33], v[32:33], v[138:139]
	v_pk_mul_f32 v[28:29], v[28:29], v[134:135]
	v_pk_mul_f32 v[24:25], v[24:25], v[130:131]
	v_pk_mul_f32 v[34:35], v[34:35], v[140:141]
	v_pk_mul_f32 v[30:31], v[30:31], v[136:137]
	v_pk_mul_f32 v[26:27], v[26:27], v[132:133]
	v_pk_mul_f32 v[22:23], v[22:23], v[128:129]
	v_pk_mul_f32 v[20:21], v[20:21], v[126:127]
	v_pk_mul_f32 v[48:49], v[48:49], v[138:139]
	v_pk_mul_f32 v[44:45], v[44:45], v[134:135]
	v_pk_mul_f32 v[40:41], v[40:41], v[130:131]
	v_pk_mul_f32 v[50:51], v[50:51], v[140:141]
	v_pk_mul_f32 v[46:47], v[46:47], v[136:137]
	v_pk_mul_f32 v[42:43], v[42:43], v[132:133]
	v_pk_mul_f32 v[38:39], v[38:39], v[128:129]
	v_pk_mul_f32 v[36:37], v[36:37], v[126:127]
	v_mov_b64_e32 v[160:161], v[2:3]

; __device__ __forceinline__ float fadd_s(float a, float b) { float r = a + b; asm volatile("" : "+v"(r)); return r; }
; __device__ __forceinline__ void vfrags(VFrags& v, lds_cptr vp) {
; #pragma unroll
;     ...
; }
; __device__ __forceinline__ void pv(f32x16 (&o)[2], const VFrags& v, const u32x4& pw0, const u32x4& pw1, const u32x4& pw2, const u32x4& pw3) {
;     ...
;     o[0] = __builtin_amdgcn_mfma_f32_32x32x16_bf16(__builtin_bit_cast(bf16x8, pw0), ATT_VF(0), o[0], 0, 0, 0);
;     o[1] = __builtin_amdgcn_mfma_f32_32x32x16_bf16(__builtin_bit_cast(bf16x8, pw0), ATT_VF(4), o[1], 0, 0, 0);
;     o[0] = __builtin_amdgcn_mfma_f32_32x32x16_bf16(__builtin_bit_cast(bf16x8, pw1), ATT_VF(1), o[0], 0, 0, 0);
;     o[1] = __builtin_amdgcn_mfma_f32_32x32x16_bf16(__builtin_bit_cast(bf16x8, pw1), ATT_VF(5), o[1], 0, 0, 0);
;     o[0] = __builtin_amdgcn_mfma_f32_32x32x16_bf16(__builtin_bit_cast(bf16x8, pw2), ATT_VF(2), o[0], 0, 0, 0);
;     o[1] = __builtin_amdgcn_mfma_f32_32x32x16_bf16(__builtin_bit_cast(bf16x8, pw2), ATT_VF(6), o[1], 0, 0, 0);
;     o[0] = __builtin_amdgcn_mfma_f32_32x32x16_bf16(__builtin_bit_cast(bf16x8, pw3), ATT_VF(3), o[0], 0, 0, 0);
;     o[1] = __builtin_amdgcn_mfma_f32_32x32x16_bf16(__builtin_bit_cast(bf16x8, pw3), ATT_VF(7), o[1], 0, 0, 0);
;     ...
; }
; __device__ __forceinline__ bool fox_pair_qs(FoxState& st, PairP& pp, lds_cptr kslotB, const bf16x8 (&qr)[4], const LAS u32x2* augB  , bool careful, int r32, int hi, LAS float* wsf) {
;     ...
;     pp.w[0] = ATT_PACK4(a0, 0, cvtpk); pp.w[1] = ATT_PACK4(a0, 8, cvtpk); pp.w[2] = ATT_PACK4(a1, 0, cvtpk); pp.w[3] = ATT_PACK4(a1, 8, cvtpk);
; #pragma unroll
;     for (int r = 0; r < 16; ++r) { b0[r] = __builtin_amdgcn_exp2f(b0[r]); b1[r] = __builtin_amdgcn_exp2f(b1[r]); sacc = fadd_s(sacc, b0[r]); sacc2 = fadd_s(sacc2, b1[r]); }
;     pp.w[4] = ATT_PACK4(b0, 0, cvtpk); pp.w[5] = ATT_PACK4(b0, 8, cvtpk); pp.w[6] = ATT_PACK4(b1, 0, cvtpk); pp.w[7] = ATT_PACK4(b1, 8, cvtpk);
;     const float ts = fadd_s(sacc, sacc2);
;     if (!careful && __any(!(ts < FOX_BIG))) return false;
;     st.l = fadd_s(st.l, ts);
;     return true;
; }
; __device__ __forceinline__ void fox_pair_pv(FoxState& st, const PairP& pp, lds_cptr vpB) {
;     { VFrags vf; vfrags(vf, vpB + 8192); pv(st.o, vf, pp.w[0], pp.w[1], pp.w[2], pp.w[3]); }
;     { VFrags vf; vfrags(vf, vpB); pv(st.o, vf, pp.w[4], pp.w[5], pp.w[6], pp.w[7]); }
; }
.LBB0_341:
	v_cvt_pk_bf16_f32 v152, v84, v100
	v_cvt_pk_bf16_f32 v153, v101, v102
	v_cvt_pk_bf16_f32 v154, v103, v104
	v_cvt_pk_bf16_f32 v155, v105, v106
	v_cvt_pk_bf16_f32 v148, v107, v108
	v_cvt_pk_bf16_f32 v149, v109, v110
	v_cvt_pk_bf16_f32 v150, v111, v112
	v_cvt_pk_bf16_f32 v151, v113, v114
	v_cvt_pk_bf16_f32 v144, v3, v4
	v_cvt_pk_bf16_f32 v145, v85, v86
	v_cvt_pk_bf16_f32 v146, v87, v88
	v_cvt_pk_bf16_f32 v147, v89, v90
	v_cvt_pk_bf16_f32 v140, v91, v92
	v_cvt_pk_bf16_f32 v141, v93, v94
	v_cvt_pk_bf16_f32 v142, v95, v96
	v_cvt_pk_bf16_f32 v143, v97, v98
	v_cvt_pk_bf16_f32 v136, v99, v68
	v_cvt_pk_bf16_f32 v137, v69, v70
	v_cvt_pk_bf16_f32 v138, v71, v72
	v_cvt_pk_bf16_f32 v139, v73, v74
	v_cvt_pk_bf16_f32 v132, v75, v76
	v_cvt_pk_bf16_f32 v133, v77, v78
	v_cvt_pk_bf16_f32 v134, v79, v80
	v_cvt_pk_bf16_f32 v135, v81, v82
	v_cvt_pk_bf16_f32 v128, v52, v53
	v_cvt_pk_bf16_f32 v129, v54, v55
	v_cvt_pk_bf16_f32 v130, v56, v57
	v_cvt_pk_bf16_f32 v131, v58, v59
	v_cvt_pk_bf16_f32 v124, v60, v61
	v_cvt_pk_bf16_f32 v125, v62, v63
	v_cvt_pk_bf16_f32 v126, v64, v65
	v_cvt_pk_bf16_f32 v127, v66, v67
	s_andn2_b64 vcc, exec, s[92:93]
	s_mov_b64 s[4:5], -1
	s_cbranch_vccnz .LBB0_344
	ds_read_b64_tr_b16 v[84:85], v190 offset:57344
	ds_read_b64_tr_b16 v[86:87], v190 offset:57856
	ds_read_b64_tr_b16 v[88:89], v190 offset:61440
	ds_read_b64_tr_b16 v[90:91], v190 offset:61952
	ds_read_b64_tr_b16 v[92:93], v190 offset:58368
	ds_read_b64_tr_b16 v[94:95], v190 offset:58880
	ds_read_b64_tr_b16 v[96:97], v190 offset:62464
	ds_read_b64_tr_b16 v[98:99], v190 offset:62976
	ds_read_b64_tr_b16 v[100:101], v190 offset:59392
	ds_read_b64_tr_b16 v[102:103], v190 offset:59904
	ds_read_b64_tr_b16 v[104:105], v190 offset:63488
	ds_read_b64_tr_b16 v[106:107], v190 offset:64000
	ds_read_b64_tr_b16 v[108:109], v190 offset:60416
	ds_read_b64_tr_b16 v[110:111], v190 offset:60928
	s_mov_b64 s[4:5], 0
	s_waitcnt lgkmcnt(10)
	v_mfma_f32_32x32x16_bf16 v[20:35], v[152:155], v[84:87], v[20:35]
	ds_read_b64_tr_b16 v[112:113], v190 offset:64512
	ds_read_b64_tr_b16 v[114:115], v190 offset:65024
	v_mfma_f32_32x32x16_bf16 v[36:51], v[152:155], v[88:91], v[36:51]
	ds_read_b64_tr_b16 v[84:85], v190 offset:49152
	ds_read_b64_tr_b16 v[86:87], v190 offset:49664
	s_waitcnt lgkmcnt(10)
	v_mfma_f32_32x32x16_bf16 v[20:35], v[148:151], v[92:95], v[20:35]
	ds_read_b64_tr_b16 v[88:89], v190 offset:53248
	ds_read_b64_tr_b16 v[90:91], v190 offset:53760
	v_mfma_f32_32x32x16_bf16 v[36:51], v[148:151], v[96:99], v[36:51]
	ds_read_b64_tr_b16 v[92:93], v190 offset:50176
	ds_read_b64_tr_b16 v[94:95], v190 offset:50688
	s_waitcnt lgkmcnt(10)
	v_mfma_f32_32x32x16_bf16 v[20:35], v[144:147], v[100:103], v[20:35]
	ds_read_b64_tr_b16 v[96:97], v190 offset:54272
	ds_read_b64_tr_b16 v[98:99], v190 offset:54784
	v_mfma_f32_32x32x16_bf16 v[36:51], v[144:147], v[104:107], v[36:51]
	ds_read_b64_tr_b16 v[100:101], v190 offset:51200
	ds_read_b64_tr_b16 v[102:103], v190 offset:51712
	s_waitcnt lgkmcnt(10)
	v_mfma_f32_32x32x16_bf16 v[20:35], v[140:143], v[108:111], v[20:35]
	ds_read_b64_tr_b16 v[104:105], v190 offset:55296
	ds_read_b64_tr_b16 v[106:107], v190 offset:55808
	v_mfma_f32_32x32x16_bf16 v[36:51], v[140:143], v[112:115], v[36:51]
	ds_read_b64_tr_b16 v[108:109], v190 offset:52224
	ds_read_b64_tr_b16 v[110:111], v190 offset:52736
	s_waitcnt lgkmcnt(10)
	v_mfma_f32_32x32x16_bf16 v[20:35], v[136:139], v[84:87], v[20:35]
	ds_read_b64_tr_b16 v[112:113], v190 offset:56320
	ds_read_b64_tr_b16 v[114:115], v190 offset:56832
	v_mfma_f32_32x32x16_bf16 v[36:51], v[136:139], v[88:91], v[36:51]
	s_waitcnt lgkmcnt(8)
	v_mfma_f32_32x32x16_bf16 v[20:35], v[132:135], v[92:95], v[20:35]
	v_mfma_f32_32x32x16_bf16 v[36:51], v[132:135], v[96:99], v[36:51]
	s_waitcnt lgkmcnt(4)
	v_mfma_f32_32x32x16_bf16 v[20:35], v[128:131], v[100:103], v[20:35]
	v_mfma_f32_32x32x16_bf16 v[36:51], v[128:131], v[104:107], v[36:51]
	s_waitcnt lgkmcnt(0)
	v_mfma_f32_32x32x16_bf16 v[20:35], v[124:127], v[108:111], v[20:35]
	v_mfma_f32_32x32x16_bf16 v[36:51], v[124:127], v[112:115], v[36:51]
	s_branch .LBB0_345

; #define LAS __attribute__((address_space(3)))
; #define ATT_WAIT_BAR() asm volatile("s_waitcnt vmcnt(0) lgkmcnt(0)\n\ts_barrier" ::: "memory")
;     bf16x8 kf[8]; kfrags(kf, kslot, r32, hi);
;     f32x16 p0, p1;
; #pragma unroll
;     for (int g = 0; g < 4; ++g) { const f32x4 c0 = ld4(ckt + 8 * g), c1 = ld4(ckt + 32 + 8 * g);
; #pragma unroll
;         for (int i = 0; i < 4; ++i) { p0[4 * g + i] = c0[i]; p1[4 * g + i] = c1[i]; } }
;     u32x4 kn = {0u, 0xBF800000u, 0xBF80BF80u, 0u}; if (hi) { kn.y = 0u; kn.z = 0u; }
;     const bf16x8 kneg = __builtin_bit_cast(bf16x8, kn);
;     p0 = __builtin_amdgcn_mfma_f32_32x32x16_bf16(kneg, st.mq, p0, 0, 0, 0);
;     p1 = __builtin_amdgcn_mfma_f32_32x32x16_bf16(kneg, st.mq, p1, 0, 0, 0);
; #pragma unroll
;     for (int d0 = 0; d0 < 4; ++d0) {
;         p0 = __builtin_amdgcn_mfma_f32_32x32x16_bf16(kf[2 * d0], qr[d0], p0, 0, 0, 0);
;         p1 = __builtin_amdgcn_mfma_f32_32x32x16_bf16(kf[2 * d0 + 1], qr[d0], p1, 0, 0, 0);
;     }
; __device__ __forceinline__ void prompt_unit_fox(const Args& a, int l, int b, int h, int qb, LAS unsigned char* lds) {
;     ...
;         ATT_WAIT_BAR();
;         if (jp >= 1) ATT_DMA2(jp - 1, slot == 2 ? 0 : slot + 1);
;         const lds_cptr kslot = (lds_cptr)lds + F_K + slot * 16384; const lds_cptr vp = vp0 + slot * 16384;
;         const LAS float* ck0 = (const LAS float*)(lds + F_CK) + (2 * jp) * 64 + 4 * hi;
;         if (pending) { fox_pair_pv(st, pp, vp0 + pslot * 16384); pending = false; }
;         if (jp < jpd) {
;             bool careful = false;
; #pragma unroll 1
;             for (int pass = 0; pass < 2; ++pass) { if (fox_pair_qs(st, pp, kslot, qr, (const LAS u32x2*)(lds + F_AUG) + (2 * jp) * 64 + r32, careful, r32, hi, wsf)) break; careful = true; }
;             if (lateB) { pending = true; pslot = slot; } else fox_pair_pv(st, pp, vp);
;         } else if (jp == jpd) {
;             if (jd & 1) { fox_tile(st, kslot + 8192, vp + 8192, qr, ck0 + 64, true, true, qlim, r32, hi, wsf); fox_tile(st, kslot, vp, qr, ck0, false, false, qlim, r32, hi, wsf); }
.LBB0_967:
	s_andn2_b64 vcc, exec, s[2:3]
	s_cbranch_vccnz .LBB0_969
	v_lshl_add_u32 v3, s75, 14, v175
	ds_read_b64_tr_b16 v[84:85], v3 offset:57344
	ds_read_b64_tr_b16 v[86:87], v3 offset:57856
	ds_read_b64_tr_b16 v[88:89], v3 offset:61440
	ds_read_b64_tr_b16 v[90:91], v3 offset:61952
	ds_read_b64_tr_b16 v[92:93], v3 offset:58368
	ds_read_b64_tr_b16 v[94:95], v3 offset:58880
	ds_read_b64_tr_b16 v[96:97], v3 offset:62464
	ds_read_b64_tr_b16 v[98:99], v3 offset:62976
	ds_read_b64_tr_b16 v[100:101], v3 offset:59392
	ds_read_b64_tr_b16 v[102:103], v3 offset:59904
	ds_read_b64_tr_b16 v[104:105], v3 offset:63488
	ds_read_b64_tr_b16 v[106:107], v3 offset:64000
	ds_read_b64_tr_b16 v[108:109], v3 offset:60416
	ds_read_b64_tr_b16 v[110:111], v3 offset:60928
	s_waitcnt lgkmcnt(10)
	v_mfma_f32_32x32x16_bf16 v[20:35], v[152:155], v[84:87], v[20:35]
	ds_read_b64_tr_b16 v[112:113], v3 offset:64512
	ds_read_b64_tr_b16 v[114:115], v3 offset:65024
	v_mfma_f32_32x32x16_bf16 v[36:51], v[152:155], v[88:91], v[36:51]
	ds_read_b64_tr_b16 v[84:85], v3 offset:49152
	ds_read_b64_tr_b16 v[86:87], v3 offset:49664
	s_waitcnt lgkmcnt(10)
	v_mfma_f32_32x32x16_bf16 v[20:35], v[148:151], v[92:95], v[20:35]
	ds_read_b64_tr_b16 v[88:89], v3 offset:53248
	ds_read_b64_tr_b16 v[90:91], v3 offset:53760
	v_mfma_f32_32x32x16_bf16 v[36:51], v[148:151], v[96:99], v[36:51]
	ds_read_b64_tr_b16 v[92:93], v3 offset:50176
	ds_read_b64_tr_b16 v[94:95], v3 offset:50688
	s_waitcnt lgkmcnt(10)
	v_mfma_f32_32x32x16_bf16 v[20:35], v[144:147], v[100:103], v[20:35]
	ds_read_b64_tr_b16 v[96:97], v3 offset:54272
	ds_read_b64_tr_b16 v[98:99], v3 offset:54784
	v_mfma_f32_32x32x16_bf16 v[36:51], v[144:147], v[104:107], v[36:51]
	ds_read_b64_tr_b16 v[100:101], v3 offset:51200
	ds_read_b64_tr_b16 v[102:103], v3 offset:51712
	s_waitcnt lgkmcnt(10)
	v_mfma_f32_32x32x16_bf16 v[20:35], v[140:143], v[108:111], v[20:35]
	ds_read_b64_tr_b16 v[104:105], v3 offset:55296
	ds_read_b64_tr_b16 v[106:107], v3 offset:55808
	v_mfma_f32_32x32x16_bf16 v[36:51], v[140:143], v[112:115], v[36:51]
	ds_read_b64_tr_b16 v[108:109], v3 offset:52224
	ds_read_b64_tr_b16 v[110:111], v3 offset:52736
	s_waitcnt lgkmcnt(10)
	v_mfma_f32_32x32x16_bf16 v[20:35], v[136:139], v[84:87], v[20:35]
	ds_read_b64_tr_b16 v[112:113], v3 offset:56320
	ds_read_b64_tr_b16 v[114:115], v3 offset:56832
	v_mfma_f32_32x32x16_bf16 v[36:51], v[136:139], v[88:91], v[36:51]
	s_waitcnt lgkmcnt(8)
	v_mfma_f32_32x32x16_bf16 v[20:35], v[132:135], v[92:95], v[20:35]
	v_mfma_f32_32x32x16_bf16 v[36:51], v[132:135], v[96:99], v[36:51]
	s_waitcnt lgkmcnt(4)
	v_mfma_f32_32x32x16_bf16 v[20:35], v[128:131], v[100:103], v[20:35]
	v_mfma_f32_32x32x16_bf16 v[36:51], v[128:131], v[104:107], v[36:51]
	s_waitcnt lgkmcnt(0)
	v_mfma_f32_32x32x16_bf16 v[20:35], v[124:127], v[108:111], v[20:35]
	v_mfma_f32_32x32x16_bf16 v[36:51], v[124:127], v[112:115], v[36:51]
.LBB0_969:
	s_add_i32 s80, s33, 0
	s_lshl_b32 s81, s78, 7
	v_add_u32_e32 v190, s33, v175
	s_cmp_ge_i32 s78, s0
	s_mov_b64 s[2:3], -1
	s_cbranch_scc0 .LBB0_980
	s_nop 11
	v_mov_b64_e32 v[66:67], v[50:51]
	v_mov_b64_e32 v[82:83], v[34:35]
	v_mov_b64_e32 v[162:163], v[158:159]
	s_cmp_lg_u32 s78, s0
	v_mov_b64_e32 v[64:65], v[48:49]
	v_mov_b64_e32 v[62:63], v[46:47]
	v_mov_b64_e32 v[60:61], v[44:45]
	v_mov_b64_e32 v[58:59], v[42:43]
	v_mov_b64_e32 v[56:57], v[40:41]
	v_mov_b64_e32 v[54:55], v[38:39]
	v_mov_b64_e32 v[52:53], v[36:37]
	v_mov_b64_e32 v[80:81], v[32:33]
	v_mov_b64_e32 v[78:79], v[30:31]
	v_mov_b64_e32 v[76:77], v[28:29]
	v_mov_b64_e32 v[74:75], v[26:27]
	v_mov_b64_e32 v[72:73], v[24:25]
	v_mov_b64_e32 v[70:71], v[22:23]
	v_mov_b64_e32 v[68:69], v[20:21]
	v_mov_b64_e32 v[160:161], v[156:157]
	v_mov_b32_e32 v194, v192
	v_mov_b32_e32 v191, v193
	s_cbranch_scc1 .LBB0_979
	v_lshl_add_u32 v196, s81, 2, v186
	s_andn2_b64 vcc, exec, s[94:95]
	v_add3_u32 v195, s80, v182, v189
	s_cbranch_vccnz .LBB0_977
	ds_read_b128 v[68:71], v196 offset:256
	ds_read_b128 v[72:75], v196 offset:288
	ds_read_b128 v[76:79], v196 offset:320
	ds_read_b128 v[80:83], v196 offset:352
	ds_read_b128 v[52:55], v196 offset:384
	ds_read_b128 v[56:59], v196 offset:416
	ds_read_b128 v[60:63], v196 offset:448
	ds_read_b128 v[64:67], v196 offset:480
	ds_read_b128 v[84:87], v195 offset:8192
	s_waitcnt lgkmcnt(5)
	v_mfma_f32_32x32x16_bf16 v[68:83], v[120:123], v[156:159], v[68:83]
	s_waitcnt lgkmcnt(0)
	v_mfma_f32_32x32x16_bf16 v[68:83], v[84:87], v[6:9], v[68:83]
	ds_read_b128 v[84:87], v195 offset:8704
	v_mfma_f32_32x32x16_bf16 v[52:67], v[120:123], v[156:159], v[52:67]
	s_waitcnt lgkmcnt(0)
	v_mfma_f32_32x32x16_bf16 v[52:67], v[84:87], v[6:9], v[52:67]
	ds_read_b128 v[84:87], v195 offset:10240
	s_waitcnt lgkmcnt(0)
	v_mfma_f32_32x32x16_bf16 v[68:83], v[84:87], v[10:13], v[68:83]
	ds_read_b128 v[84:87], v195 offset:10752
	s_waitcnt lgkmcnt(0)
	v_mfma_f32_32x32x16_bf16 v[52:67], v[84:87], v[10:13], v[52:67]
	ds_read_b128 v[84:87], v195 offset:12288
	s_waitcnt lgkmcnt(0)
	v_mfma_f32_32x32x16_bf16 v[68:83], v[84:87], v[14:17], v[68:83]
	ds_read_b128 v[84:87], v195 offset:12800
	s_waitcnt lgkmcnt(0)
	v_mfma_f32_32x32x16_bf16 v[52:67], v[84:87], v[14:17], v[52:67]
	ds_read_b128 v[84:87], v195 offset:14336
	s_waitcnt lgkmcnt(0)
	v_mfma_f32_32x32x16_bf16 v[68:83], v[84:87], v[116:119], v[68:83]
	ds_read_b128 v[84:87], v195 offset:14848
	s_waitcnt lgkmcnt(0)
; #define LAS __attribute__((address_space(3)))
; __device__ __forceinline__ int crow(int r, int hi) { return (r & 3) + 8 * (r >> 2) + 4 * hi; }
; __device__ __forceinline__ float swap_max(float m) { auto rr = __builtin_amdgcn_permlane32_swap(__float_as_uint(m), __float_as_uint(m), false, false); return fmaxf(__uint_as_float(rr[0]), __uint_as_float(rr[1])); }
; __device__ __forceinline__ float max3f(float a, float b, float c) { return __builtin_fmaxf(__builtin_fmaxf(a, b), c); }
; __device__ __forceinline__ float fadd_s(float a, float b) { float r = a + b; asm volatile("" : "+v"(r)); return r; }
; #define ATT_LDS_WAIT() asm volatile("s_waitcnt lgkmcnt(0)" ::: "memory")
;     ...
;     if (masked) {
;         asm volatile("; masked tile" ::: "memory");
; #pragma unroll
;         for (int r = 0; r < 16; ++r) { const int kv = crow(r, hi); if (kv >= qlim) p0[r] = NEG; if (kv + 32 >= qlim) p1[r] = NEG; }
;     }
;     float rm = max3f(p0[0], p1[0], p0[1]), rm2 = max3f(p1[1], p0[2], p1[2]);
; #pragma unroll
;     for (int r = 3; r < 15; r += 2) { rm = max3f(rm, p0[r], p1[r]); rm2 = max3f(rm2, p0[r + 1], p1[r + 1]); }
;     rm = max3f(rm, p0[15], p1[15]); rm = swap_max(max3f(rm, rm2, rm2));
;     if (first || __any(rm > FOX_THR)) {
;         const float dl = first ? rm : fmaxf(rm, 0.f);
;         st.m += dl; st.mq = make_mq(st.m, hi);
; #pragma unroll
;         for (int r = 0; r < 16; ++r) { p0[r] -= dl; p1[r] -= dl; }
;         if (!first) {
;             const float f = __builtin_amdgcn_exp2f(-dl);
;             st.l *= f;
;             if (hi == 0) wsf[r32] = f;
;             ATT_LDS_WAIT();
; #pragma unroll
;             for (int g = 0; g < 4; ++g) { const f32x4 fv = *(const LAS f32x4*)(wsf + 8 * g + 4 * hi);
; #pragma unroll
;                 for (int i = 0; i < 4; ++i) { st.o[0][4 * g + i] *= fv[i]; st.o[1][4 * g + i] *= fv[i]; } }
;         }
;     }
;     __builtin_amdgcn_sched_barrier(0);
;     VFrags vf; vfrags(vf, vp);
;     float sacc = 0.f, sacc2 = 0.f;
; #pragma unroll
;     for (int r = 0; r < 16; ++r) { p0[r] = __builtin_amdgcn_exp2f(p0[r]); p1[r] = __builtin_amdgcn_exp2f(p1[r]); sacc = fadd_s(sacc, p0[r]); sacc2 = fadd_s(sacc2, p1[r]); }
	v_mfma_f32_32x32x16_bf16 v[52:67], v[84:87], v[116:119], v[52:67]
	s_and_b64 vcc, s[70:71], s[66:67]
	s_nop 7
	v_cndmask_b32_e32 v82, v82, v18, vcc
	s_and_b64 vcc, vcc, s[62:63]
	v_cndmask_b32_e32 v81, v81, v18, vcc
	s_and_b64 vcc, vcc, s[58:59]
	v_cndmask_b32_e32 v80, v80, v18, vcc
	s_and_b64 vcc, vcc, s[54:55]
	v_cndmask_b32_e32 v79, v79, v18, vcc
	s_and_b64 vcc, vcc, s[50:51]
	v_cndmask_b32_e32 v78, v78, v18, vcc
	s_and_b64 vcc, vcc, s[46:47]
	v_cndmask_b32_e32 v77, v77, v18, vcc
	s_and_b64 vcc, vcc, s[42:43]
	v_cndmask_b32_e32 v76, v76, v18, vcc
	s_and_b64 vcc, vcc, s[38:39]
	v_cndmask_b32_e32 v75, v75, v18, vcc
	s_and_b64 vcc, vcc, s[34:35]
	v_cndmask_b32_e32 v74, v74, v18, vcc
	s_and_b64 vcc, vcc, s[28:29]
	v_cndmask_b32_e32 v73, v73, v18, vcc
	s_and_b64 vcc, vcc, s[24:25]
	v_cndmask_b32_e64 v3, v68, v18, s[8:9]
	v_cndmask_b32_e32 v72, v72, v18, vcc
	s_and_b64 vcc, vcc, s[20:21]
	v_cndmask_b32_e64 v3, v3, v68, s[12:13]
	v_cndmask_b32_e64 v4, v18, v69, s[12:13]
	v_cndmask_b32_e32 v71, v71, v18, vcc
	s_and_b64 vcc, vcc, s[16:17]
	v_cndmask_b32_e32 v69, v69, v4, vcc
	v_cndmask_b32_e32 v68, v68, v3, vcc
	v_cndmask_b32_e32 v70, v70, v18, vcc
	s_and_b64 vcc, s[72:73], s[68:69]
	v_cndmask_b32_e32 v66, v66, v18, vcc
	s_and_b64 vcc, vcc, s[64:65]
	v_cndmask_b32_e32 v65, v65, v18, vcc
	s_and_b64 vcc, vcc, s[60:61]
	v_cndmask_b32_e32 v64, v64, v18, vcc
	s_and_b64 vcc, vcc, s[56:57]
	v_cndmask_b32_e32 v63, v63, v18, vcc
	s_and_b64 vcc, vcc, s[52:53]
	v_cndmask_b32_e32 v62, v62, v18, vcc
	s_and_b64 vcc, vcc, s[48:49]
	v_cndmask_b32_e32 v61, v61, v18, vcc
	s_and_b64 vcc, vcc, s[44:45]
	v_cndmask_b32_e32 v60, v60, v18, vcc
	s_and_b64 vcc, vcc, s[40:41]
	v_cndmask_b32_e32 v59, v59, v18, vcc
	s_and_b64 vcc, vcc, s[36:37]
	v_cndmask_b32_e32 v58, v58, v18, vcc
	s_and_b64 vcc, vcc, s[30:31]
	v_cndmask_b32_e32 v57, v57, v18, vcc
	s_and_b64 vcc, vcc, s[26:27]
	v_cndmask_b32_e32 v56, v56, v18, vcc
	s_and_b64 vcc, vcc, s[22:23]
	v_cndmask_b32_e32 v55, v55, v18, vcc
	s_and_b64 vcc, vcc, s[18:19]
	v_cndmask_b32_e32 v54, v54, v18, vcc
	s_and_b64 vcc, vcc, s[14:15]
	v_cndmask_b32_e32 v53, v53, v18, vcc
	s_and_b64 vcc, vcc, s[10:11]
	v_cndmask_b32_e32 v52, v52, v18, vcc
	v_max_f32_e32 v3, v68, v68
	v_max_f32_e32 v4, v52, v52
	v_max_f32_e32 v3, v3, v4
	v_max3_f32 v4, v53, v70, v54
	v_max3_f32 v3, v3, v69, v71
	v_max3_f32 v4, v4, v72, v56
	v_max3_f32 v3, v3, v55, v73
	v_max3_f32 v4, v4, v74, v58
	v_max3_f32 v3, v3, v57, v75
	v_max3_f32 v4, v4, v76, v60
	v_max3_f32 v3, v3, v59, v77
	v_max3_f32 v4, v4, v78, v62
	v_max3_f32 v3, v3, v61, v79
	v_cndmask_b32_e64 v83, v83, v18, s[70:71]
	v_max3_f32 v4, v4, v80, v64
	v_max3_f32 v3, v3, v63, v81
	v_cndmask_b32_e64 v67, v67, v18, s[72:73]
	v_max3_f32 v4, v4, v82, v66
	v_max3_f32 v3, v3, v65, v83
	v_max3_f32 v3, v3, v67, v4
	v_mov_b32_e32 v4, v3
	s_nop 1
	v_permlane32_swap_b32_e32 v3, v4
	v_max_f32_e32 v4, v4, v4
	v_max_f32_e32 v3, v3, v3
	v_max_f32_e32 v84, v3, v4
	v_add_f32_e32 v191, v193, v84
	v_cvt_pk_bf16_f32 v3, v191, 0
	v_lshlrev_b32_e32 v3, 16, v3
	v_sub_f32_e32 v4, v191, v3
	v_cvt_pk_bf16_f32 v85, v4, 0
	v_lshlrev_b32_e32 v85, 16, v85
	v_sub_f32_e32 v4, v4, v85
	v_cvt_pk_bf16_f32 v3, 1.0, v3
	v_cvt_pk_bf16_f32 v4, v85, v4
	v_cndmask_b32_e64 v4, 0, v4, s[6:7]
	v_cndmask_b32_e64 v3, 0, v3, s[6:7]
	v_sub_f32_e32 v68, v68, v84
	v_sub_f32_e32 v112, v52, v84
	v_sub_f32_e32 v69, v69, v84
	v_sub_f32_e32 v113, v53, v84
	v_sub_f32_e32 v70, v70, v84
	v_sub_f32_e32 v114, v54, v84
	v_sub_f32_e32 v71, v71, v84
	v_sub_f32_e32 v115, v55, v84
	v_sub_f32_e32 v72, v72, v84
	v_sub_f32_e32 v56, v56, v84
	v_sub_f32_e32 v73, v73, v84
	v_sub_f32_e32 v57, v57, v84
	v_sub_f32_e32 v74, v74, v84
	v_sub_f32_e32 v58, v58, v84
	v_sub_f32_e32 v75, v75, v84
	v_sub_f32_e32 v59, v59, v84
	v_sub_f32_e32 v76, v76, v84
	v_sub_f32_e32 v60, v60, v84
	v_sub_f32_e32 v77, v77, v84
	v_sub_f32_e32 v61, v61, v84
	v_sub_f32_e32 v78, v78, v84
	v_sub_f32_e32 v62, v62, v84
	v_sub_f32_e32 v79, v79, v84
	v_sub_f32_e32 v63, v63, v84
	v_sub_f32_e32 v80, v80, v84
	v_sub_f32_e32 v64, v64, v84
	v_sub_f32_e32 v81, v81, v84
	v_sub_f32_e32 v65, v65, v84
	v_sub_f32_e32 v82, v82, v84
	v_sub_f32_e32 v66, v66, v84
	v_sub_f32_e32 v83, v83, v84
	v_sub_f32_e32 v67, v67, v84
	v_exp_f32_e32 v68, v68
	v_exp_f32_e32 v164, v112
	v_exp_f32_e32 v69, v69
	v_exp_f32_e32 v165, v113
	v_add_f32_e32 v112, 0, v68
	v_exp_f32_e32 v70, v70
	ds_read_b64_tr_b16 v[52:53], v190 offset:57344
	ds_read_b64_tr_b16 v[54:55], v190 offset:57856
	ds_read_b64_tr_b16 v[84:85], v190 offset:58368
	ds_read_b64_tr_b16 v[86:87], v190 offset:58880
	ds_read_b64_tr_b16 v[88:89], v190 offset:59392
	ds_read_b64_tr_b16 v[90:91], v190 offset:59904
	ds_read_b64_tr_b16 v[92:93], v190 offset:60416
	ds_read_b64_tr_b16 v[94:95], v190 offset:60928
	ds_read_b64_tr_b16 v[96:97], v190 offset:61440
	ds_read_b64_tr_b16 v[98:99], v190 offset:61952
	ds_read_b64_tr_b16 v[100:101], v190 offset:62464
	ds_read_b64_tr_b16 v[102:103], v190 offset:62976
	ds_read_b64_tr_b16 v[104:105], v190 offset:63488
	ds_read_b64_tr_b16 v[106:107], v190 offset:64000
	ds_read_b64_tr_b16 v[108:109], v190 offset:64512
	ds_read_b64_tr_b16 v[110:111], v190 offset:65024
	v_exp_f32_e32 v166, v114
	v_add_f32_e32 v160, 0, v164
	v_add_f32_e32 v112, v112, v69
	v_exp_f32_e32 v71, v71
	v_exp_f32_e32 v167, v115
	v_add_f32_e32 v113, v160, v165
	v_add_f32_e32 v112, v112, v70
	v_exp_f32_e32 v72, v72
	v_add_f32_e32 v113, v113, v166
	v_exp_f32_e32 v56, v56
	v_add_f32_e32 v112, v112, v71
	v_exp_f32_e32 v73, v73
	v_add_f32_e32 v113, v113, v167
	v_exp_f32_e32 v57, v57
	v_add_f32_e32 v112, v112, v72
	v_exp_f32_e32 v74, v74
	v_add_f32_e32 v113, v113, v56
	v_exp_f32_e32 v58, v58
; __device__ __forceinline__ int crow(int r, int hi) { return (r & 3) + 8 * (r >> 2) + 4 * hi; }
; __device__ __forceinline__ unsigned cvtpk(float lo, float hi) { f32x2 v = {lo, hi}; bf16x2_t b = __builtin_convertvector(v, bf16x2_t); return __builtin_bit_cast(unsigned, b); }
;     bf16x8 kf[8]; kfrags(kf, kslot, r32, hi);
;     f32x16 p0, p1;
; #pragma unroll
;     for (int g = 0; g < 4; ++g) { const f32x4 c0 = ld4(ckt + 8 * g), c1 = ld4(ckt + 32 + 8 * g);
; #pragma unroll
;         for (int i = 0; i < 4; ++i) { p0[4 * g + i] = c0[i]; p1[4 * g + i] = c1[i]; } }
;     u32x4 kn = {0u, 0xBF800000u, 0xBF80BF80u, 0u}; if (hi) { kn.y = 0u; kn.z = 0u; }
;     const bf16x8 kneg = __builtin_bit_cast(bf16x8, kn);
;     p0 = __builtin_amdgcn_mfma_f32_32x32x16_bf16(kneg, st.mq, p0, 0, 0, 0);
;     p1 = __builtin_amdgcn_mfma_f32_32x32x16_bf16(kneg, st.mq, p1, 0, 0, 0);
; #pragma unroll
;     for (int d0 = 0; d0 < 4; ++d0) {
;         p0 = __builtin_amdgcn_mfma_f32_32x32x16_bf16(kf[2 * d0], qr[d0], p0, 0, 0, 0);
;         p1 = __builtin_amdgcn_mfma_f32_32x32x16_bf16(kf[2 * d0 + 1], qr[d0], p1, 0, 0, 0);
;     }
;     __builtin_amdgcn_sched_barrier(0);
;     if (LEVEL == 2) { asm volatile("" :: "v"(p0), "v"(p1)); return; }
;     if (masked) {
;         asm volatile("; masked tile" ::: "memory");
; #pragma unroll
;         for (int r = 0; r < 16; ++r) { const int kv = crow(r, hi); if (kv >= qlim) p0[r] = NEG; if (kv + 32 >= qlim) p1[r] = NEG; }
;     }
;     float rm = max3f(p0[0], p1[0], p0[1]), rm2 = max3f(p1[1], p0[2], p1[2]);
; #pragma unroll
;     for (int r = 3; r < 15; r += 2) { rm = max3f(rm, p0[r], p1[r]); rm2 = max3f(rm2, p0[r + 1], p1[r + 1]); }
;     rm = max3f(rm, p0[15], p1[15]); rm = swap_max(max3f(rm, rm2, rm2));
;     if (first || __any(rm > FOX_THR)) {
;     ...
;     VFrags vf; vfrags(vf, vp);
;     float sacc = 0.f, sacc2 = 0.f;
; #pragma unroll
;     for (int r = 0; r < 16; ++r) { p0[r] = __builtin_amdgcn_exp2f(p0[r]); p1[r] = __builtin_amdgcn_exp2f(p1[r]); sacc = fadd_s(sacc, p0[r]); sacc2 = fadd_s(sacc2, p1[r]); }
;     st.l = fadd_s(st.l, fadd_s(sacc, sacc2));
;     const u32x4 pw0 = ATT_PACK4(p0, 0, cvtpk), pw1 = ATT_PACK4(p0, 8, cvtpk), pw2 = ATT_PACK4(p1, 0, cvtpk), pw3 = ATT_PACK4(p1, 8, cvtpk);
;     __builtin_amdgcn_sched_barrier(0);
;     ...
;     pv(st.o, vf, pw0, pw1, pw2, pw3);
	v_add_f32_e32 v112, v112, v73
	v_exp_f32_e32 v75, v75
	v_add_f32_e32 v113, v113, v57
	v_exp_f32_e32 v59, v59
	v_add_f32_e32 v112, v112, v74
	v_exp_f32_e32 v76, v76
	v_add_f32_e32 v113, v113, v58
	v_exp_f32_e32 v60, v60
	v_add_f32_e32 v112, v112, v75
	v_exp_f32_e32 v77, v77
	v_add_f32_e32 v113, v113, v59
	v_exp_f32_e32 v61, v61
	v_add_f32_e32 v112, v76, v112
	v_exp_f32_e32 v78, v78
	v_add_f32_e32 v113, v60, v113
	v_exp_f32_e32 v62, v62
	v_add_f32_e32 v112, v77, v112
	v_exp_f32_e32 v79, v79
	v_add_f32_e32 v113, v61, v113
	v_exp_f32_e32 v63, v63
	v_add_f32_e32 v112, v78, v112
	v_exp_f32_e32 v80, v80
	v_add_f32_e32 v113, v62, v113
	v_exp_f32_e32 v64, v64
	v_add_f32_e32 v112, v79, v112
	v_exp_f32_e32 v81, v81
	v_add_f32_e32 v113, v63, v113
	v_exp_f32_e32 v65, v65
	v_add_f32_e32 v112, v80, v112
	v_exp_f32_e32 v82, v82
	v_add_f32_e32 v113, v64, v113
	v_exp_f32_e32 v66, v66
	v_add_f32_e32 v112, v81, v112
	v_exp_f32_e32 v83, v83
	v_add_f32_e32 v113, v65, v113
	v_exp_f32_e32 v67, v67
	v_add_f32_e32 v112, v82, v112
	v_add_f32_e32 v113, v66, v113
	v_add_f32_e32 v112, v83, v112
	v_add_f32_e32 v113, v67, v113
	v_cvt_pk_bf16_f32 v114, v72, v73
	v_add_f32_e32 v112, v112, v113
	v_cvt_pk_bf16_f32 v113, v70, v71
	v_add_f32_e32 v194, v192, v112
	v_cvt_pk_bf16_f32 v112, v68, v69
	v_cvt_pk_bf16_f32 v115, v74, v75
	v_cvt_pk_bf16_f32 v160, v76, v77
	v_cvt_pk_bf16_f32 v161, v78, v79
	v_cvt_pk_bf16_f32 v162, v80, v81
	v_cvt_pk_bf16_f32 v163, v82, v83
	v_cvt_pk_bf16_f32 v164, v164, v165
	v_cvt_pk_bf16_f32 v165, v166, v167
	v_cvt_pk_bf16_f32 v166, v56, v57
	v_cvt_pk_bf16_f32 v167, v58, v59
	v_cvt_pk_bf16_f32 v198, v60, v61
	v_cvt_pk_bf16_f32 v199, v62, v63
	v_cvt_pk_bf16_f32 v200, v64, v65
	v_cvt_pk_bf16_f32 v201, v66, v67
	s_waitcnt lgkmcnt(6)
	v_mfma_f32_32x32x16_bf16 v[68:83], v[112:115], v[52:55], v[20:35]
	v_mfma_f32_32x32x16_bf16 v[52:67], v[112:115], v[96:99], v[36:51]
	v_mfma_f32_32x32x16_bf16 v[68:83], v[160:163], v[84:87], v[68:83]
	s_waitcnt lgkmcnt(4)
	v_mfma_f32_32x32x16_bf16 v[52:67], v[160:163], v[100:103], v[52:67]
	v_mfma_f32_32x32x16_bf16 v[68:83], v[164:167], v[88:91], v[68:83]
	s_waitcnt lgkmcnt(2)
	v_mfma_f32_32x32x16_bf16 v[52:67], v[164:167], v[104:107], v[52:67]
	v_mfma_f32_32x32x16_bf16 v[68:83], v[198:201], v[92:95], v[68:83]
	ds_read_b128 v[84:87], v196
	ds_read_b128 v[88:91], v196 offset:32
	ds_read_b128 v[92:95], v196 offset:64
	ds_read_b128 v[96:99], v196 offset:96
	s_waitcnt lgkmcnt(0)
	v_mfma_f32_32x32x16_bf16 v[52:67], v[198:201], v[108:111], v[52:67]
	ds_read_b128 v[100:103], v196 offset:128
	ds_read_b128 v[104:107], v196 offset:160
	ds_read_b128 v[108:111], v196 offset:192
	ds_read_b128 v[112:115], v196 offset:224
	ds_read_b128 v[160:163], v195
	ds_read_b128 v[164:167], v195 offset:512
	v_mfma_f32_32x32x16_bf16 v[84:99], v[120:123], v[2:5], v[84:99]
	s_waitcnt lgkmcnt(1)
	v_mfma_f32_32x32x16_bf16 v[100:115], v[120:123], v[2:5], v[100:115]
	v_mfma_f32_32x32x16_bf16 v[84:99], v[160:163], v[6:9], v[84:99]
	s_waitcnt lgkmcnt(0)
	v_mfma_f32_32x32x16_bf16 v[100:115], v[164:167], v[6:9], v[100:115]
	ds_read_b128 v[160:163], v195 offset:2048
	ds_read_b128 v[164:167], v195 offset:2560
	s_waitcnt lgkmcnt(0)
	v_mfma_f32_32x32x16_bf16 v[84:99], v[160:163], v[10:13], v[84:99]
	v_mfma_f32_32x32x16_bf16 v[100:115], v[164:167], v[10:13], v[100:115]
	ds_read_b128 v[160:163], v195 offset:4096
	ds_read_b128 v[164:167], v195 offset:4608
	s_waitcnt lgkmcnt(0)
	v_mfma_f32_32x32x16_bf16 v[84:99], v[160:163], v[14:17], v[84:99]
	v_mfma_f32_32x32x16_bf16 v[100:115], v[164:167], v[14:17], v[100:115]
	ds_read_b128 v[160:163], v195 offset:6144
	ds_read_b128 v[164:167], v195 offset:6656
	s_waitcnt lgkmcnt(0)
	v_mfma_f32_32x32x16_bf16 v[84:99], v[160:163], v[116:119], v[84:99]
	v_mfma_f32_32x32x16_bf16 v[100:115], v[164:167], v[116:119], v[100:115]
	s_nop 11
	v_max_f32_e32 v160, v100, v100
	v_max_f32_e32 v161, v84, v84
	v_max_f32_e32 v160, v161, v160
	v_max3_f32 v161, v101, v86, v102
	v_max3_f32 v160, v160, v85, v87
	v_max3_f32 v161, v161, v88, v104
	v_max3_f32 v160, v160, v103, v89
	v_max3_f32 v161, v161, v90, v106
	v_max3_f32 v160, v160, v105, v91
	v_max3_f32 v161, v161, v92, v108
	v_max3_f32 v160, v160, v107, v93
	v_max3_f32 v161, v161, v94, v110
	v_max3_f32 v160, v160, v109, v95
	v_max3_f32 v161, v161, v96, v112
	v_max3_f32 v160, v160, v111, v97
	v_max3_f32 v161, v161, v98, v114
	v_max3_f32 v160, v160, v113, v99
	v_max3_f32 v160, v160, v115, v161
	v_mov_b32_e32 v161, v160
	s_nop 1
	v_permlane32_swap_b32_e32 v160, v161
	v_max_f32_e32 v161, v161, v161
	v_max_f32_e32 v160, v160, v160
	v_max_f32_e32 v160, v160, v161
	s_mov_b32 s2, 0x41000000
	v_cmp_lt_f32_e32 vcc, s2, v160
	s_cbranch_vccz .LBB0_976
; #define LAS __attribute__((address_space(3)))
; #define ATT_LDS_WAIT() asm volatile("s_waitcnt lgkmcnt(0)" ::: "memory")
;     ...
;     if (first || __any(rm > FOX_THR)) {
;         const float dl = first ? rm : fmaxf(rm, 0.f);
;         st.m += dl; st.mq = make_mq(st.m, hi);
; #pragma unroll
;         for (int r = 0; r < 16; ++r) { p0[r] -= dl; p1[r] -= dl; }
;         if (!first) {
;             const float f = __builtin_amdgcn_exp2f(-dl);
;             st.l *= f;
;             if (hi == 0) wsf[r32] = f;
;             ATT_LDS_WAIT();
; #pragma unroll
;             for (int g = 0; g < 4; ++g) { const f32x4 fv = *(const LAS f32x4*)(wsf + 8 * g + 4 * hi);
; #pragma unroll
;                 for (int i = 0; i < 4; ++i) { st.o[0][4 * g + i] *= fv[i]; st.o[1][4 * g + i] *= fv[i]; } }
;         }
	v_max_f32_e32 v160, 0, v160
	v_exp_f32_e64 v161, -v160
	s_and_saveexec_b64 s[2:3], s[6:7]
	ds_write_b32 v184, v161
	s_or_b64 exec, exec, s[2:3]
	v_add_f32_e32 v191, v191, v160
	v_cvt_pk_bf16_f32 v3, v191, 0
	v_lshlrev_b32_e32 v3, 16, v3
	v_sub_f32_e32 v4, v191, v3
	v_cvt_pk_bf16_f32 v162, v4, 0
	v_lshlrev_b32_e32 v162, 16, v162
	v_sub_f32_e32 v4, v4, v162
	s_waitcnt lgkmcnt(0)
	v_add_u32_e32 v197, s89, v174
	v_cvt_pk_bf16_f32 v4, v162, v4
	v_pk_add_f32 v[84:85], v[84:85], v[160:161] op_sel_hi:[1,0] neg_lo:[0,1] neg_hi:[0,1]
	v_pk_add_f32 v[100:101], v[100:101], v[160:161] op_sel_hi:[1,0] neg_lo:[0,1] neg_hi:[0,1]
	v_pk_add_f32 v[86:87], v[86:87], v[160:161] op_sel_hi:[1,0] neg_lo:[0,1] neg_hi:[0,1]
	v_pk_add_f32 v[102:103], v[102:103], v[160:161] op_sel_hi:[1,0] neg_lo:[0,1] neg_hi:[0,1]
	v_pk_add_f32 v[88:89], v[88:89], v[160:161] op_sel_hi:[1,0] neg_lo:[0,1] neg_hi:[0,1]
	v_pk_add_f32 v[104:105], v[104:105], v[160:161] op_sel_hi:[1,0] neg_lo:[0,1] neg_hi:[0,1]
	v_pk_add_f32 v[90:91], v[90:91], v[160:161] op_sel_hi:[1,0] neg_lo:[0,1] neg_hi:[0,1]
	v_pk_add_f32 v[106:107], v[106:107], v[160:161] op_sel_hi:[1,0] neg_lo:[0,1] neg_hi:[0,1]
	v_pk_add_f32 v[92:93], v[92:93], v[160:161] op_sel_hi:[1,0] neg_lo:[0,1] neg_hi:[0,1]
	v_pk_add_f32 v[108:109], v[108:109], v[160:161] op_sel_hi:[1,0] neg_lo:[0,1] neg_hi:[0,1]
	v_pk_add_f32 v[94:95], v[94:95], v[160:161] op_sel_hi:[1,0] neg_lo:[0,1] neg_hi:[0,1]
	v_pk_add_f32 v[110:111], v[110:111], v[160:161] op_sel_hi:[1,0] neg_lo:[0,1] neg_hi:[0,1]
	v_pk_add_f32 v[96:97], v[96:97], v[160:161] op_sel_hi:[1,0] neg_lo:[0,1] neg_hi:[0,1]
	v_pk_add_f32 v[112:113], v[112:113], v[160:161] op_sel_hi:[1,0] neg_lo:[0,1] neg_hi:[0,1]
	v_pk_add_f32 v[98:99], v[98:99], v[160:161] op_sel_hi:[1,0] neg_lo:[0,1] neg_hi:[0,1]
	v_pk_add_f32 v[114:115], v[114:115], v[160:161] op_sel_hi:[1,0] neg_lo:[0,1] neg_hi:[0,1]
	v_mul_f32_e32 v194, v194, v161
	ds_read_b128 v[160:163], v197
	ds_read_b128 v[164:167], v197 offset:32
	ds_read_b128 v[198:201], v197 offset:64
	ds_read_b128 v[202:205], v197 offset:96
	v_cvt_pk_bf16_f32 v3, 1.0, v3
	v_cndmask_b32_e64 v4, 0, v4, s[6:7]
	v_cndmask_b32_e64 v3, 0, v3, s[6:7]
	s_waitcnt lgkmcnt(1)
	v_pk_mul_f32 v[76:77], v[76:77], v[198:199]
	s_waitcnt lgkmcnt(0)
	v_pk_mul_f32 v[80:81], v[80:81], v[202:203]
	v_pk_mul_f32 v[72:73], v[72:73], v[164:165]
	v_pk_mul_f32 v[82:83], v[82:83], v[204:205]
	v_pk_mul_f32 v[78:79], v[78:79], v[200:201]
	v_pk_mul_f32 v[74:75], v[74:75], v[166:167]
	v_pk_mul_f32 v[70:71], v[70:71], v[162:163]
	v_pk_mul_f32 v[68:69], v[68:69], v[160:161]
	v_pk_mul_f32 v[64:65], v[64:65], v[202:203]
	v_pk_mul_f32 v[60:61], v[60:61], v[198:199]
	v_pk_mul_f32 v[56:57], v[56:57], v[164:165]
	v_pk_mul_f32 v[66:67], v[66:67], v[204:205]
	v_pk_mul_f32 v[62:63], v[62:63], v[200:201]
	v_pk_mul_f32 v[58:59], v[58:59], v[166:167]
	v_pk_mul_f32 v[54:55], v[54:55], v[162:163]
	v_pk_mul_f32 v[52:53], v[52:53], v[160:161]

; __device__ __forceinline__ int crow(int r, int hi) { return (r & 3) + 8 * (r >> 2) + 4 * hi; }
; __device__ __forceinline__ float swap_max(float m) { auto rr = __builtin_amdgcn_permlane32_swap(__float_as_uint(m), __float_as_uint(m), false, false); return fmaxf(__uint_as_float(rr[0]), __uint_as_float(rr[1])); }
; __device__ __forceinline__ float max3f(float a, float b, float c) { return __builtin_fmaxf(__builtin_fmaxf(a, b), c); }
;     bf16x8 kf[8]; kfrags(kf, kslot, r32, hi);
;     f32x16 p0, p1;
; #pragma unroll
;     for (int g = 0; g < 4; ++g) { const f32x4 c0 = ld4(ckt + 8 * g), c1 = ld4(ckt + 32 + 8 * g);
; #pragma unroll
;         for (int i = 0; i < 4; ++i) { p0[4 * g + i] = c0[i]; p1[4 * g + i] = c1[i]; } }
;     u32x4 kn = {0u, 0xBF800000u, 0xBF80BF80u, 0u}; if (hi) { kn.y = 0u; kn.z = 0u; }
;     const bf16x8 kneg = __builtin_bit_cast(bf16x8, kn);
;     p0 = __builtin_amdgcn_mfma_f32_32x32x16_bf16(kneg, st.mq, p0, 0, 0, 0);
;     p1 = __builtin_amdgcn_mfma_f32_32x32x16_bf16(kneg, st.mq, p1, 0, 0, 0);
; #pragma unroll
;     for (int d0 = 0; d0 < 4; ++d0) {
;         p0 = __builtin_amdgcn_mfma_f32_32x32x16_bf16(kf[2 * d0], qr[d0], p0, 0, 0, 0);
;         p1 = __builtin_amdgcn_mfma_f32_32x32x16_bf16(kf[2 * d0 + 1], qr[d0], p1, 0, 0, 0);
;     }
;     __builtin_amdgcn_sched_barrier(0);
;     if (LEVEL == 2) { asm volatile("" :: "v"(p0), "v"(p1)); return; }
;     if (masked) {
;         asm volatile("; masked tile" ::: "memory");
; #pragma unroll
;         for (int r = 0; r < 16; ++r) { const int kv = crow(r, hi); if (kv >= qlim) p0[r] = NEG; if (kv + 32 >= qlim) p1[r] = NEG; }
;     }
;     float rm = max3f(p0[0], p1[0], p0[1]), rm2 = max3f(p1[1], p0[2], p1[2]);
; #pragma unroll
;     for (int r = 3; r < 15; r += 2) { rm = max3f(rm, p0[r], p1[r]); rm2 = max3f(rm2, p0[r + 1], p1[r + 1]); }
;     rm = max3f(rm, p0[15], p1[15]); rm = swap_max(max3f(rm, rm2, rm2));
;     if (first || __any(rm > FOX_THR)) {
;         const float dl = first ? rm : fmaxf(rm, 0.f);
;         st.m += dl; st.mq = make_mq(st.m, hi);
; #pragma unroll
;         for (int r = 0; r < 16; ++r) { p0[r] -= dl; p1[r] -= dl; }
.LBB0_977:
	s_and_b64 vcc, exec, s[2:3]
	s_cbranch_vccz .LBB0_979
	s_nop 7
	ds_read_b128 v[68:71], v196
	ds_read_b128 v[72:75], v196 offset:32
	ds_read_b128 v[76:79], v196 offset:64
	ds_read_b128 v[80:83], v196 offset:96
	ds_read_b128 v[52:55], v196 offset:128
	ds_read_b128 v[56:59], v196 offset:160
	ds_read_b128 v[60:63], v196 offset:192
	ds_read_b128 v[64:67], v196 offset:224
	ds_read_b128 v[84:87], v195
	s_waitcnt lgkmcnt(5)
	v_mfma_f32_32x32x16_bf16 v[68:83], v[120:123], v[156:159], v[68:83]
	s_waitcnt lgkmcnt(0)
	v_mfma_f32_32x32x16_bf16 v[68:83], v[84:87], v[6:9], v[68:83]
	ds_read_b128 v[84:87], v195 offset:512
	v_mfma_f32_32x32x16_bf16 v[52:67], v[120:123], v[156:159], v[52:67]
	s_waitcnt lgkmcnt(0)
	v_mfma_f32_32x32x16_bf16 v[52:67], v[84:87], v[6:9], v[52:67]
	ds_read_b128 v[84:87], v195 offset:2048
	s_waitcnt lgkmcnt(0)
	v_mfma_f32_32x32x16_bf16 v[68:83], v[84:87], v[10:13], v[68:83]
	ds_read_b128 v[84:87], v195 offset:2560
	s_waitcnt lgkmcnt(0)
	v_mfma_f32_32x32x16_bf16 v[52:67], v[84:87], v[10:13], v[52:67]
	ds_read_b128 v[84:87], v195 offset:4096
	s_waitcnt lgkmcnt(0)
	v_mfma_f32_32x32x16_bf16 v[68:83], v[84:87], v[14:17], v[68:83]
	ds_read_b128 v[84:87], v195 offset:4608
	s_waitcnt lgkmcnt(0)
	v_mfma_f32_32x32x16_bf16 v[52:67], v[84:87], v[14:17], v[52:67]
	ds_read_b128 v[84:87], v195 offset:6144
	s_waitcnt lgkmcnt(0)
	v_mfma_f32_32x32x16_bf16 v[68:83], v[84:87], v[116:119], v[68:83]
	ds_read_b128 v[84:87], v195 offset:6656
	s_waitcnt lgkmcnt(0)
	v_mfma_f32_32x32x16_bf16 v[52:67], v[84:87], v[116:119], v[52:67]
	s_and_b64 vcc, s[70:71], s[66:67]
	s_nop 7
	v_cndmask_b32_e32 v82, v82, v18, vcc
	s_and_b64 vcc, vcc, s[62:63]
	v_cndmask_b32_e32 v81, v81, v18, vcc
	s_and_b64 vcc, vcc, s[58:59]
	v_cndmask_b32_e32 v80, v80, v18, vcc
	s_and_b64 vcc, vcc, s[54:55]
	v_cndmask_b32_e32 v79, v79, v18, vcc
	s_and_b64 vcc, vcc, s[50:51]
	v_cndmask_b32_e32 v78, v78, v18, vcc
	s_and_b64 vcc, vcc, s[46:47]
	v_cndmask_b32_e32 v77, v77, v18, vcc
	s_and_b64 vcc, vcc, s[42:43]
	v_cndmask_b32_e32 v76, v76, v18, vcc
	s_and_b64 vcc, vcc, s[38:39]
	v_cndmask_b32_e32 v75, v75, v18, vcc
	s_and_b64 vcc, vcc, s[34:35]
	v_cndmask_b32_e32 v74, v74, v18, vcc
	s_and_b64 vcc, vcc, s[28:29]
	v_cndmask_b32_e32 v73, v73, v18, vcc
	s_and_b64 vcc, vcc, s[24:25]
	v_cndmask_b32_e64 v3, v68, v18, s[8:9]
	v_cndmask_b32_e32 v72, v72, v18, vcc
	s_and_b64 vcc, vcc, s[20:21]
	v_cndmask_b32_e64 v3, v3, v68, s[12:13]
	v_cndmask_b32_e64 v4, v18, v69, s[12:13]
	v_cndmask_b32_e32 v71, v71, v18, vcc
	s_and_b64 vcc, vcc, s[16:17]
	v_cndmask_b32_e32 v69, v69, v4, vcc
	v_cndmask_b32_e32 v68, v68, v3, vcc
	v_cndmask_b32_e32 v70, v70, v18, vcc
	s_and_b64 vcc, s[72:73], s[68:69]
	v_cndmask_b32_e32 v66, v66, v18, vcc
	s_and_b64 vcc, vcc, s[64:65]
	v_cndmask_b32_e32 v65, v65, v18, vcc
	s_and_b64 vcc, vcc, s[60:61]
	v_cndmask_b32_e32 v64, v64, v18, vcc
	s_and_b64 vcc, vcc, s[56:57]
	v_cndmask_b32_e32 v63, v63, v18, vcc
	s_and_b64 vcc, vcc, s[52:53]
	v_cndmask_b32_e32 v62, v62, v18, vcc
	s_and_b64 vcc, vcc, s[48:49]
	v_cndmask_b32_e32 v61, v61, v18, vcc
	s_and_b64 vcc, vcc, s[44:45]
	v_cndmask_b32_e32 v60, v60, v18, vcc
	s_and_b64 vcc, vcc, s[40:41]
	v_cndmask_b32_e32 v59, v59, v18, vcc
	s_and_b64 vcc, vcc, s[36:37]
	v_cndmask_b32_e32 v58, v58, v18, vcc
	s_and_b64 vcc, vcc, s[30:31]
	v_cndmask_b32_e32 v57, v57, v18, vcc
	s_and_b64 vcc, vcc, s[26:27]
	v_cndmask_b32_e32 v56, v56, v18, vcc
	s_and_b64 vcc, vcc, s[22:23]
	v_cndmask_b32_e32 v55, v55, v18, vcc
	s_and_b64 vcc, vcc, s[18:19]
	v_cndmask_b32_e32 v54, v54, v18, vcc
	s_and_b64 vcc, vcc, s[14:15]
	v_cndmask_b32_e32 v53, v53, v18, vcc
	s_and_b64 vcc, vcc, s[10:11]
	v_cndmask_b32_e32 v52, v52, v18, vcc
	v_max_f32_e32 v3, v68, v68
	v_max_f32_e32 v4, v52, v52
	v_max_f32_e32 v3, v3, v4
	v_max3_f32 v4, v53, v70, v54
	v_max3_f32 v3, v3, v69, v71
	v_max3_f32 v4, v4, v72, v56
	v_max3_f32 v3, v3, v55, v73
	v_max3_f32 v4, v4, v74, v58
	v_max3_f32 v3, v3, v57, v75
	v_max3_f32 v4, v4, v76, v60
	v_max3_f32 v3, v3, v59, v77
	v_max3_f32 v4, v4, v78, v62
	v_max3_f32 v3, v3, v61, v79
	v_cndmask_b32_e64 v83, v83, v18, s[70:71]
	v_max3_f32 v4, v4, v80, v64
	v_max3_f32 v3, v3, v63, v81
	v_cndmask_b32_e64 v67, v67, v18, s[72:73]
	v_max3_f32 v4, v4, v82, v66
	v_max3_f32 v3, v3, v65, v83
	v_max3_f32 v3, v3, v67, v4
	v_mov_b32_e32 v4, v3
	s_nop 1
	v_permlane32_swap_b32_e32 v3, v4
	v_max_f32_e32 v4, v4, v4
	v_max_f32_e32 v3, v3, v3
	v_max_f32_e32 v84, v3, v4
	v_add_f32_e32 v191, v193, v84
	v_cvt_pk_bf16_f32 v3, v191, 0
	v_lshlrev_b32_e32 v3, 16, v3
	v_sub_f32_e32 v4, v191, v3
	v_cvt_pk_bf16_f32 v85, v4, 0
	v_lshlrev_b32_e32 v85, 16, v85
	v_sub_f32_e32 v4, v4, v85
	v_cvt_pk_bf16_f32 v3, 1.0, v3
	v_cvt_pk_bf16_f32 v4, v85, v4
	v_sub_f32_e32 v68, v68, v84
	v_sub_f32_e32 v69, v69, v84
	v_sub_f32_e32 v70, v70, v84
; #define LAS __attribute__((address_space(3)))
; __device__ __forceinline__ unsigned cvtpk(float lo, float hi) { f32x2 v = {lo, hi}; bf16x2_t b = __builtin_convertvector(v, bf16x2_t); return __builtin_bit_cast(unsigned, b); }
; __device__ __forceinline__ float fadd_s(float a, float b) { float r = a + b; asm volatile("" : "+v"(r)); return r; }
; #define ATT_LDS_WAIT() asm volatile("s_waitcnt lgkmcnt(0)" ::: "memory")
; #define ATT_PACK4(P, B, F) (u32x4){F(P[B], P[B + 1]), F(P[B + 2], P[B + 3]), F(P[B + 4], P[B + 5]), F(P[B + 6], P[B + 7])}
;     ...
;         for (int r = 0; r < 16; ++r) { p0[r] -= dl; p1[r] -= dl; }
;         if (!first) {
;             const float f = __builtin_amdgcn_exp2f(-dl);
;             st.l *= f;
;             if (hi == 0) wsf[r32] = f;
;             ATT_LDS_WAIT();
; #pragma unroll
;             for (int g = 0; g < 4; ++g) { const f32x4 fv = *(const LAS f32x4*)(wsf + 8 * g + 4 * hi);
; #pragma unroll
;                 for (int i = 0; i < 4; ++i) { st.o[0][4 * g + i] *= fv[i]; st.o[1][4 * g + i] *= fv[i]; } }
;         }
;     }
;     __builtin_amdgcn_sched_barrier(0);
;     VFrags vf; vfrags(vf, vp);
;     float sacc = 0.f, sacc2 = 0.f;
; #pragma unroll
;     for (int r = 0; r < 16; ++r) { p0[r] = __builtin_amdgcn_exp2f(p0[r]); p1[r] = __builtin_amdgcn_exp2f(p1[r]); sacc = fadd_s(sacc, p0[r]); sacc2 = fadd_s(sacc2, p1[r]); }
;     st.l = fadd_s(st.l, fadd_s(sacc, sacc2));
;     const u32x4 pw0 = ATT_PACK4(p0, 0, cvtpk), pw1 = ATT_PACK4(p0, 8, cvtpk), pw2 = ATT_PACK4(p1, 0, cvtpk), pw3 = ATT_PACK4(p1, 8, cvtpk);
;     __builtin_amdgcn_sched_barrier(0);
;     ...
;     pv(st.o, vf, pw0, pw1, pw2, pw3);
	v_sub_f32_e32 v71, v71, v84
	v_sub_f32_e32 v72, v72, v84
	v_sub_f32_e32 v56, v56, v84
	v_sub_f32_e32 v73, v73, v84
	v_sub_f32_e32 v57, v57, v84
	v_sub_f32_e32 v74, v74, v84
	v_sub_f32_e32 v58, v58, v84
	v_sub_f32_e32 v75, v75, v84
	v_sub_f32_e32 v59, v59, v84
	v_sub_f32_e32 v76, v76, v84
	v_sub_f32_e32 v60, v60, v84
	v_sub_f32_e32 v77, v77, v84
	v_sub_f32_e32 v61, v61, v84
	v_sub_f32_e32 v78, v78, v84
	v_sub_f32_e32 v62, v62, v84
	v_sub_f32_e32 v79, v79, v84
	v_sub_f32_e32 v63, v63, v84
	v_sub_f32_e32 v80, v80, v84
	v_sub_f32_e32 v64, v64, v84
	v_sub_f32_e32 v81, v81, v84
	v_sub_f32_e32 v65, v65, v84
	v_sub_f32_e32 v82, v82, v84
	v_sub_f32_e32 v66, v66, v84
	v_sub_f32_e32 v83, v83, v84
	v_sub_f32_e32 v67, v67, v84
	v_cndmask_b32_e64 v4, 0, v4, s[6:7]
	v_cndmask_b32_e64 v3, 0, v3, s[6:7]
	v_sub_f32_e32 v112, v52, v84
	v_sub_f32_e32 v113, v53, v84
	v_sub_f32_e32 v114, v54, v84
	v_sub_f32_e32 v115, v55, v84
	v_exp_f32_e32 v68, v68
	v_exp_f32_e32 v164, v112
	v_exp_f32_e32 v69, v69
	v_exp_f32_e32 v165, v113
	v_add_f32_e32 v112, 0, v68
	v_exp_f32_e32 v70, v70
	ds_read_b64_tr_b16 v[52:53], v190 offset:49152
	ds_read_b64_tr_b16 v[54:55], v190 offset:49664
	ds_read_b64_tr_b16 v[84:85], v190 offset:50176
	ds_read_b64_tr_b16 v[86:87], v190 offset:50688
	ds_read_b64_tr_b16 v[88:89], v190 offset:51200
	ds_read_b64_tr_b16 v[90:91], v190 offset:51712
	ds_read_b64_tr_b16 v[92:93], v190 offset:52224
	ds_read_b64_tr_b16 v[94:95], v190 offset:52736
	ds_read_b64_tr_b16 v[96:97], v190 offset:53248
	ds_read_b64_tr_b16 v[98:99], v190 offset:53760
	ds_read_b64_tr_b16 v[100:101], v190 offset:54272
	ds_read_b64_tr_b16 v[102:103], v190 offset:54784
	ds_read_b64_tr_b16 v[104:105], v190 offset:55296
	ds_read_b64_tr_b16 v[106:107], v190 offset:55808
	ds_read_b64_tr_b16 v[108:109], v190 offset:56320
	ds_read_b64_tr_b16 v[110:111], v190 offset:56832
	v_exp_f32_e32 v166, v114
	v_add_f32_e32 v160, 0, v164
	v_add_f32_e32 v112, v112, v69
	v_exp_f32_e32 v71, v71
	v_exp_f32_e32 v167, v115
	v_add_f32_e32 v113, v160, v165
	v_add_f32_e32 v112, v112, v70
	v_exp_f32_e32 v72, v72
	v_add_f32_e32 v113, v113, v166
	v_exp_f32_e32 v56, v56
	v_add_f32_e32 v112, v112, v71
	v_exp_f32_e32 v73, v73
	v_add_f32_e32 v113, v113, v167
	v_exp_f32_e32 v57, v57
	v_add_f32_e32 v112, v112, v72
	v_exp_f32_e32 v74, v74
	v_add_f32_e32 v113, v113, v56
	v_exp_f32_e32 v58, v58
	v_add_f32_e32 v112, v112, v73
	v_exp_f32_e32 v75, v75
	v_add_f32_e32 v113, v113, v57
	v_exp_f32_e32 v59, v59
	v_add_f32_e32 v112, v112, v74
	v_exp_f32_e32 v76, v76
	v_add_f32_e32 v113, v113, v58
	v_exp_f32_e32 v60, v60
	v_add_f32_e32 v112, v112, v75
	v_exp_f32_e32 v77, v77
	v_add_f32_e32 v113, v113, v59
	v_exp_f32_e32 v61, v61
	v_add_f32_e32 v112, v76, v112
	v_exp_f32_e32 v78, v78
	v_add_f32_e32 v113, v60, v113
	v_exp_f32_e32 v62, v62
	v_add_f32_e32 v112, v77, v112
	v_exp_f32_e32 v79, v79
	v_add_f32_e32 v113, v61, v113
	v_exp_f32_e32 v63, v63
	v_add_f32_e32 v112, v78, v112
	v_exp_f32_e32 v80, v80
	v_add_f32_e32 v113, v62, v113
	v_exp_f32_e32 v64, v64
	v_add_f32_e32 v112, v79, v112
	v_exp_f32_e32 v81, v81
	v_add_f32_e32 v113, v63, v113
	v_exp_f32_e32 v65, v65
	v_add_f32_e32 v112, v80, v112
	v_exp_f32_e32 v82, v82
	v_add_f32_e32 v113, v64, v113
	v_exp_f32_e32 v66, v66
	v_add_f32_e32 v112, v81, v112
	v_exp_f32_e32 v83, v83
	v_add_f32_e32 v113, v65, v113
	v_exp_f32_e32 v67, v67
	v_add_f32_e32 v112, v82, v112
	v_add_f32_e32 v113, v66, v113
	v_add_f32_e32 v112, v83, v112
	v_add_f32_e32 v113, v67, v113
	v_cvt_pk_bf16_f32 v160, v76, v77
	v_add_f32_e32 v112, v112, v113
	v_cvt_pk_bf16_f32 v161, v78, v79
	v_add_f32_e32 v194, v192, v112
	v_cvt_pk_bf16_f32 v162, v80, v81
	v_cvt_pk_bf16_f32 v163, v82, v83
	v_cvt_pk_bf16_f32 v112, v68, v69
	v_cvt_pk_bf16_f32 v113, v70, v71
	v_cvt_pk_bf16_f32 v114, v72, v73
	v_cvt_pk_bf16_f32 v115, v74, v75
	v_cvt_pk_bf16_f32 v164, v164, v165
	v_cvt_pk_bf16_f32 v165, v166, v167
	v_cvt_pk_bf16_f32 v166, v56, v57
	v_cvt_pk_bf16_f32 v167, v58, v59
	v_cvt_pk_bf16_f32 v196, v60, v61
	v_cvt_pk_bf16_f32 v197, v62, v63
	v_cvt_pk_bf16_f32 v198, v64, v65
	v_cvt_pk_bf16_f32 v199, v66, v67
	s_waitcnt lgkmcnt(6)
	v_mfma_f32_32x32x16_bf16 v[68:83], v[112:115], v[52:55], v[20:35]
	v_mfma_f32_32x32x16_bf16 v[52:67], v[112:115], v[96:99], v[36:51]
	v_mfma_f32_32x32x16_bf16 v[68:83], v[160:163], v[84:87], v[68:83]
	s_waitcnt lgkmcnt(4)
	v_mfma_f32_32x32x16_bf16 v[52:67], v[160:163], v[100:103], v[52:67]
	v_mov_b64_e32 v[162:163], v[4:5]
	v_mov_b64_e32 v[160:161], v[2:3]
	v_mfma_f32_32x32x16_bf16 v[68:83], v[164:167], v[88:91], v[68:83]
	s_waitcnt lgkmcnt(2)
	v_mfma_f32_32x32x16_bf16 v[52:67], v[164:167], v[104:107], v[52:67]
	v_mfma_f32_32x32x16_bf16 v[68:83], v[196:199], v[92:95], v[68:83]
	s_waitcnt lgkmcnt(0)
	v_mfma_f32_32x32x16_bf16 v[52:67], v[196:199], v[108:111], v[52:67]

; #define LAS __attribute__((address_space(3)))
; __device__ __forceinline__ bool fox_pair_qs(FoxState& st, PairP& pp, lds_cptr kslotB, const bf16x8 (&qr)[4], const LAS u32x2* augB  , bool careful, int r32, int hi, LAS float* wsf) {
;     bf16x8 kfA[8], kfB[8]; kfrags(kfA, kslotB + 8192, r32, hi); kfrags(kfB, kslotB, r32, hi);
;     const u32x2 t0 = augB[64], t1 = augB[96], t2 = augB[0], t3 = augB[32];
;     const f32x16 zz = {};
;     f32x16 a0, a1, b0, b1;
;     a0 = __builtin_amdgcn_mfma_f32_32x32x16_bf16(__builtin_bit_cast(bf16x8, (u32x4){t0.x, t0.y, 0xBF80BF80u, 0u}), st.mq, zz, 0, 0, 0);
;     a1 = __builtin_amdgcn_mfma_f32_32x32x16_bf16(__builtin_bit_cast(bf16x8, (u32x4){t1.x, t1.y, 0xBF80BF80u, 0u}), st.mq, zz, 0, 0, 0);
;     b0 = __builtin_amdgcn_mfma_f32_32x32x16_bf16(__builtin_bit_cast(bf16x8, (u32x4){t2.x, t2.y, 0xBF80BF80u, 0u}), st.mq, zz, 0, 0, 0);
;     b1 = __builtin_amdgcn_mfma_f32_32x32x16_bf16(__builtin_bit_cast(bf16x8, (u32x4){t3.x, t3.y, 0xBF80BF80u, 0u}), st.mq, zz, 0, 0, 0);
; #pragma unroll
;     for (int d0 = 0; d0 < 4; ++d0) {
;         a0 = __builtin_amdgcn_mfma_f32_32x32x16_bf16(kfA[2 * d0], qr[d0], a0, 0, 0, 0); a1 = __builtin_amdgcn_mfma_f32_32x32x16_bf16(kfA[2 * d0 + 1], qr[d0], a1, 0, 0, 0);
;         b0 = __builtin_amdgcn_mfma_f32_32x32x16_bf16(kfB[2 * d0], qr[d0], b0, 0, 0, 0); b1 = __builtin_amdgcn_mfma_f32_32x32x16_bf16(kfB[2 * d0 + 1], qr[d0], b1, 0, 0, 0);
;     }
.LBB0_982:
	ds_read_b64 v[56:57], v124 offset:512
	ds_read_b64 v[60:61], v124 offset:768
	ds_read_b64 v[52:53], v124
	ds_read_b64 v[70:71], v124 offset:256
	ds_read_b128 v[196:199], v125 offset:8192
	ds_read_b128 v[200:203], v125 offset:8704
	ds_read_b128 v[204:207], v125
	ds_read_b128 v[208:211], v125 offset:512
	ds_read_b128 v[220:223], v125 offset:10240
	ds_read_b128 v[224:227], v125 offset:10752
	ds_read_b128 v[228:231], v125 offset:2048
	ds_read_b128 v[232:235], v125 offset:2560
	v_mov_b64_e32 v[58:59], s[86:87]
	v_mov_b64_e32 v[62:63], s[86:87]
	v_mov_b64_e32 v[54:55], s[86:87]
	v_mov_b64_e32 v[72:73], s[86:87]
	s_xor_b64 s[2:3], s[82:83], -1
	s_and_b64 vcc, exec, s[2:3]
	s_waitcnt lgkmcnt(10)
	v_mfma_f32_32x32x16_bf16 v[84:99], v[56:59], v[160:163], 0
	v_mfma_f32_32x32x16_bf16 v[100:115], v[60:63], v[160:163], 0
	s_waitcnt lgkmcnt(8)
	v_mfma_f32_32x32x16_bf16 v[52:67], v[52:55], v[160:163], 0
	v_mfma_f32_32x32x16_bf16 v[68:83], v[70:73], v[160:163], 0
	s_waitcnt lgkmcnt(6)
	v_mfma_f32_32x32x16_bf16 v[84:99], v[196:199], v[6:9], v[84:99]
	ds_read_b128 v[196:199], v125 offset:12288
	v_mfma_f32_32x32x16_bf16 v[100:115], v[200:203], v[6:9], v[100:115]
	ds_read_b128 v[200:203], v125 offset:12800
	s_waitcnt lgkmcnt(6)
	v_mfma_f32_32x32x16_bf16 v[52:67], v[204:207], v[6:9], v[52:67]
	ds_read_b128 v[204:207], v125 offset:4096
	v_mfma_f32_32x32x16_bf16 v[68:83], v[208:211], v[6:9], v[68:83]
	ds_read_b128 v[208:211], v125 offset:4608
	s_waitcnt lgkmcnt(6)
	v_mfma_f32_32x32x16_bf16 v[84:99], v[220:223], v[10:13], v[84:99]
	ds_read_b128 v[220:223], v125 offset:14336
	v_mfma_f32_32x32x16_bf16 v[100:115], v[224:227], v[10:13], v[100:115]
	ds_read_b128 v[224:227], v125 offset:14848
	s_waitcnt lgkmcnt(6)
	v_mfma_f32_32x32x16_bf16 v[52:67], v[228:231], v[10:13], v[52:67]
	ds_read_b128 v[228:231], v125 offset:6144
	v_mfma_f32_32x32x16_bf16 v[68:83], v[232:235], v[10:13], v[68:83]
	ds_read_b128 v[232:235], v125 offset:6656
	s_waitcnt lgkmcnt(6)
	v_mfma_f32_32x32x16_bf16 v[84:99], v[196:199], v[14:17], v[84:99]
	v_mfma_f32_32x32x16_bf16 v[100:115], v[200:203], v[14:17], v[100:115]
	s_waitcnt lgkmcnt(4)
	v_mfma_f32_32x32x16_bf16 v[52:67], v[204:207], v[14:17], v[52:67]
	v_mfma_f32_32x32x16_bf16 v[68:83], v[208:211], v[14:17], v[68:83]
	s_waitcnt lgkmcnt(2)
	v_mfma_f32_32x32x16_bf16 v[84:99], v[220:223], v[116:119], v[84:99]
	v_mfma_f32_32x32x16_bf16 v[100:115], v[224:227], v[116:119], v[100:115]
	s_waitcnt lgkmcnt(0)
	v_mfma_f32_32x32x16_bf16 v[52:67], v[228:231], v[116:119], v[52:67]
	v_mfma_f32_32x32x16_bf16 v[68:83], v[232:235], v[116:119], v[68:83]
	s_nop 2
	s_cbranch_vccnz .LBB0_986
; #define LAS __attribute__((address_space(3)))
; __device__ __forceinline__ float swap_max(float m) { auto rr = __builtin_amdgcn_permlane32_swap(__float_as_uint(m), __float_as_uint(m), false, false); return fmaxf(__uint_as_float(rr[0]), __uint_as_float(rr[1])); }
; __device__ __forceinline__ float max3f(float a, float b, float c) { return __builtin_fmaxf(__builtin_fmaxf(a, b), c); }
; #define ATT_LDS_WAIT() asm volatile("s_waitcnt lgkmcnt(0)" ::: "memory")
; __device__ __forceinline__ bool fox_pair_qs(FoxState& st, PairP& pp, lds_cptr kslotB, const bf16x8 (&qr)[4], const LAS u32x2* augB  , bool careful, int r32, int hi, LAS float* wsf) {
;     ...
;     if (careful) {
;         asm volatile("; careful pass: move the reference" ::: "memory");
;         float rm = max3f(a0[0], a1[0], b0[0]), rm2 = max3f(b1[0], a0[1], a1[1]);
;         rm = max3f(rm, b0[1], b1[1]);
; #pragma unroll
;         for (int r = 2; r < 16; ++r) { rm = max3f(rm, a0[r], a1[r]); rm2 = max3f(rm2, b0[r], b1[r]); }
;         rm = swap_max(max3f(rm, rm2, rm2));
;         const float dl = fmaxf(rm, 0.f);
;         st.m += dl; st.mq = make_mq(st.m, hi);
; #pragma unroll
;         for (int r = 0; r < 16; ++r) { a0[r] -= dl; a1[r] -= dl; b0[r] -= dl; b1[r] -= dl; }
;         const float f = __builtin_amdgcn_exp2f(-dl);
;         st.l *= f;
;         if (hi == 0) wsf[r32] = f;
;         ATT_LDS_WAIT();
; #pragma unroll
;         for (int g = 0; g < 4; ++g) { const f32x4 fv = *(const LAS f32x4*)(wsf + 8 * g + 4 * hi);
; #pragma unroll
;             for (int i = 0; i < 4; ++i) { st.o[0][4 * g + i] *= fv[i]; st.o[1][4 * g + i] *= fv[i]; } }
;     }
	s_nop 4
	v_max_f32_e32 v3, v100, v100
	v_max_f32_e32 v4, v84, v84
	v_max_f32_e32 v3, v4, v3
	s_nop 2
	v_max3_f32 v4, v68, v85, v101
	v_max3_f32 v3, v3, v52, v53
	v_max3_f32 v3, v3, v69, v86
	v_max3_f32 v4, v4, v54, v70
	v_max3_f32 v3, v3, v102, v87
	v_max3_f32 v4, v4, v55, v71
	v_max3_f32 v3, v3, v103, v88
	v_max3_f32 v4, v4, v56, v72
	v_max3_f32 v3, v3, v104, v89
	v_max3_f32 v4, v4, v57, v73
	v_max3_f32 v3, v3, v105, v90
	v_max3_f32 v4, v4, v58, v74
	v_max3_f32 v3, v3, v106, v91
	v_max3_f32 v4, v4, v59, v75
	v_max3_f32 v3, v3, v107, v92
	v_max3_f32 v4, v4, v60, v76
	v_max3_f32 v3, v3, v108, v93
	v_max3_f32 v4, v4, v61, v77
	v_max3_f32 v3, v3, v109, v94
	v_max3_f32 v4, v4, v62, v78
	v_max3_f32 v3, v3, v110, v95
	v_max3_f32 v4, v4, v63, v79
	v_max3_f32 v3, v3, v111, v96
	v_max3_f32 v4, v4, v64, v80
	v_max3_f32 v3, v3, v112, v97
	v_max3_f32 v4, v4, v65, v81
	v_max3_f32 v3, v3, v113, v98
	v_max3_f32 v4, v4, v66, v82
	v_max3_f32 v3, v3, v114, v99
	v_max3_f32 v4, v4, v67, v83
	v_max3_f32 v3, v3, v115, v4
	v_mov_b32_e32 v4, v3
	s_nop 1
	v_permlane32_swap_b32_e32 v3, v4
	v_max3_f32 v126, v3, v4, 0
	v_exp_f32_e64 v127, -v126
	s_and_saveexec_b64 vcc, s[6:7]
	ds_write_b32 v184, v127
	s_or_b64 exec, exec, vcc
	v_add_f32_e32 v191, v191, v126
	v_cvt_pk_bf16_f32 v3, v191, 0
	v_lshlrev_b32_e32 v3, 16, v3
	v_sub_f32_e32 v4, v191, v3
	v_cvt_pk_bf16_f32 v128, v4, 0
	v_lshlrev_b32_e32 v128, 16, v128
	v_sub_f32_e32 v4, v4, v128
	s_waitcnt lgkmcnt(0)
	v_add_u32_e32 v138, s89, v174
	v_cvt_pk_bf16_f32 v4, v128, v4
	v_sub_f32_e32 v99, v99, v126
	v_sub_f32_e32 v98, v98, v126
	v_sub_f32_e32 v97, v97, v126
	v_sub_f32_e32 v96, v96, v126
	v_sub_f32_e32 v95, v95, v126
	v_sub_f32_e32 v94, v94, v126
	v_sub_f32_e32 v93, v93, v126
	v_sub_f32_e32 v92, v92, v126
	v_sub_f32_e32 v91, v91, v126
	v_sub_f32_e32 v90, v90, v126
	v_sub_f32_e32 v89, v89, v126
	v_sub_f32_e32 v88, v88, v126
	v_sub_f32_e32 v87, v87, v126
	v_sub_f32_e32 v86, v86, v126
	v_sub_f32_e32 v85, v85, v126
	v_sub_f32_e32 v84, v84, v126
	v_sub_f32_e32 v115, v115, v126
	v_sub_f32_e32 v114, v114, v126
	v_sub_f32_e32 v113, v113, v126
	v_sub_f32_e32 v112, v112, v126
	v_sub_f32_e32 v111, v111, v126
	v_sub_f32_e32 v110, v110, v126
	v_sub_f32_e32 v109, v109, v126
	v_sub_f32_e32 v108, v108, v126
	v_sub_f32_e32 v107, v107, v126
	v_sub_f32_e32 v106, v106, v126
	v_sub_f32_e32 v105, v105, v126
	v_sub_f32_e32 v104, v104, v126
	v_sub_f32_e32 v103, v103, v126
	v_sub_f32_e32 v102, v102, v126
	v_sub_f32_e32 v101, v101, v126
	v_sub_f32_e32 v100, v100, v126
	v_sub_f32_e32 v67, v67, v126
	v_sub_f32_e32 v66, v66, v126
	v_sub_f32_e32 v65, v65, v126
	v_sub_f32_e32 v64, v64, v126
	v_sub_f32_e32 v63, v63, v126
	v_sub_f32_e32 v62, v62, v126
	v_sub_f32_e32 v61, v61, v126
	v_sub_f32_e32 v60, v60, v126
	v_sub_f32_e32 v59, v59, v126
	v_sub_f32_e32 v58, v58, v126
	v_sub_f32_e32 v57, v57, v126
	v_sub_f32_e32 v56, v56, v126
	v_sub_f32_e32 v55, v55, v126
	v_sub_f32_e32 v54, v54, v126
	v_sub_f32_e32 v53, v53, v126
	v_sub_f32_e32 v52, v52, v126
	v_sub_f32_e32 v83, v83, v126
	v_sub_f32_e32 v82, v82, v126
	v_sub_f32_e32 v81, v81, v126
	v_sub_f32_e32 v80, v80, v126
	v_sub_f32_e32 v79, v79, v126
	v_sub_f32_e32 v78, v78, v126
	v_sub_f32_e32 v77, v77, v126
	v_sub_f32_e32 v76, v76, v126
	v_sub_f32_e32 v75, v75, v126
	v_sub_f32_e32 v74, v74, v126
	v_sub_f32_e32 v73, v73, v126
	v_sub_f32_e32 v72, v72, v126
	v_sub_f32_e32 v71, v71, v126
	v_sub_f32_e32 v70, v70, v126
	v_sub_f32_e32 v69, v69, v126
	v_sub_f32_e32 v68, v68, v126
	v_mul_f32_e32 v194, v194, v127
	ds_read_b128 v[126:129], v138
	ds_read_b128 v[130:133], v138 offset:32
	ds_read_b128 v[134:137], v138 offset:64
	ds_read_b128 v[138:141], v138 offset:96
	v_cvt_pk_bf16_f32 v3, 1.0, v3
	v_cndmask_b32_e64 v4, 0, v4, s[6:7]
	v_cndmask_b32_e64 v3, 0, v3, s[6:7]
	v_mov_b64_e32 v[162:163], v[4:5]
	s_waitcnt lgkmcnt(0)
	v_pk_mul_f32 v[32:33], v[32:33], v[138:139]
	v_pk_mul_f32 v[28:29], v[28:29], v[134:135]
	v_pk_mul_f32 v[24:25], v[24:25], v[130:131]
	v_pk_mul_f32 v[34:35], v[34:35], v[140:141]
	v_pk_mul_f32 v[30:31], v[30:31], v[136:137]
	v_pk_mul_f32 v[26:27], v[26:27], v[132:133]
	v_pk_mul_f32 v[22:23], v[22:23], v[128:129]
	v_pk_mul_f32 v[20:21], v[20:21], v[126:127]
	v_pk_mul_f32 v[48:49], v[48:49], v[138:139]
	v_pk_mul_f32 v[44:45], v[44:45], v[134:135]
	v_pk_mul_f32 v[40:41], v[40:41], v[130:131]
	v_pk_mul_f32 v[50:51], v[50:51], v[140:141]
	v_pk_mul_f32 v[46:47], v[46:47], v[136:137]
	v_pk_mul_f32 v[42:43], v[42:43], v[132:133]
	v_pk_mul_f32 v[38:39], v[38:39], v[128:129]
	v_pk_mul_f32 v[36:37], v[36:37], v[126:127]
	v_mov_b64_e32 v[160:161], v[2:3]

; __device__ __forceinline__ float fadd_s(float a, float b) { float r = a + b; asm volatile("" : "+v"(r)); return r; }
; __device__ __forceinline__ void vfrags(VFrags& v, lds_cptr vp) {
; #pragma unroll
;     ...
; }
; __device__ __forceinline__ void pv(f32x16 (&o)[2], const VFrags& v, const u32x4& pw0, const u32x4& pw1, const u32x4& pw2, const u32x4& pw3) {
;     ...
;     o[0] = __builtin_amdgcn_mfma_f32_32x32x16_bf16(__builtin_bit_cast(bf16x8, pw0), ATT_VF(0), o[0], 0, 0, 0);
;     o[1] = __builtin_amdgcn_mfma_f32_32x32x16_bf16(__builtin_bit_cast(bf16x8, pw0), ATT_VF(4), o[1], 0, 0, 0);
;     o[0] = __builtin_amdgcn_mfma_f32_32x32x16_bf16(__builtin_bit_cast(bf16x8, pw1), ATT_VF(1), o[0], 0, 0, 0);
;     o[1] = __builtin_amdgcn_mfma_f32_32x32x16_bf16(__builtin_bit_cast(bf16x8, pw1), ATT_VF(5), o[1], 0, 0, 0);
;     o[0] = __builtin_amdgcn_mfma_f32_32x32x16_bf16(__builtin_bit_cast(bf16x8, pw2), ATT_VF(2), o[0], 0, 0, 0);
;     o[1] = __builtin_amdgcn_mfma_f32_32x32x16_bf16(__builtin_bit_cast(bf16x8, pw2), ATT_VF(6), o[1], 0, 0, 0);
;     o[0] = __builtin_amdgcn_mfma_f32_32x32x16_bf16(__builtin_bit_cast(bf16x8, pw3), ATT_VF(3), o[0], 0, 0, 0);
;     o[1] = __builtin_amdgcn_mfma_f32_32x32x16_bf16(__builtin_bit_cast(bf16x8, pw3), ATT_VF(7), o[1], 0, 0, 0);
;     ...
; }
; __device__ __forceinline__ bool fox_pair_qs(FoxState& st, PairP& pp, lds_cptr kslotB, const bf16x8 (&qr)[4], const LAS u32x2* augB  , bool careful, int r32, int hi, LAS float* wsf) {
;     ...
;     pp.w[0] = ATT_PACK4(a0, 0, cvtpk); pp.w[1] = ATT_PACK4(a0, 8, cvtpk); pp.w[2] = ATT_PACK4(a1, 0, cvtpk); pp.w[3] = ATT_PACK4(a1, 8, cvtpk);
; #pragma unroll
;     for (int r = 0; r < 16; ++r) { b0[r] = __builtin_amdgcn_exp2f(b0[r]); b1[r] = __builtin_amdgcn_exp2f(b1[r]); sacc = fadd_s(sacc, b0[r]); sacc2 = fadd_s(sacc2, b1[r]); }
;     pp.w[4] = ATT_PACK4(b0, 0, cvtpk); pp.w[5] = ATT_PACK4(b0, 8, cvtpk); pp.w[6] = ATT_PACK4(b1, 0, cvtpk); pp.w[7] = ATT_PACK4(b1, 8, cvtpk);
;     const float ts = fadd_s(sacc, sacc2);
;     if (!careful && __any(!(ts < FOX_BIG))) return false;
;     st.l = fadd_s(st.l, ts);
;     return true;
; }
; __device__ __forceinline__ void fox_pair_pv(FoxState& st, const PairP& pp, lds_cptr vpB) {
;     { VFrags vf; vfrags(vf, vpB + 8192); pv(st.o, vf, pp.w[0], pp.w[1], pp.w[2], pp.w[3]); }
;     { VFrags vf; vfrags(vf, vpB); pv(st.o, vf, pp.w[4], pp.w[5], pp.w[6], pp.w[7]); }
; }
.LBB0_993:
	v_cvt_pk_bf16_f32 v152, v84, v100
	v_cvt_pk_bf16_f32 v153, v101, v102
	v_cvt_pk_bf16_f32 v154, v103, v104
	v_cvt_pk_bf16_f32 v155, v105, v106
	v_cvt_pk_bf16_f32 v148, v107, v108
	v_cvt_pk_bf16_f32 v149, v109, v110
	v_cvt_pk_bf16_f32 v150, v111, v112
	v_cvt_pk_bf16_f32 v151, v113, v114
	v_cvt_pk_bf16_f32 v144, v3, v4
	v_cvt_pk_bf16_f32 v145, v85, v86
	v_cvt_pk_bf16_f32 v146, v87, v88
	v_cvt_pk_bf16_f32 v147, v89, v90
	v_cvt_pk_bf16_f32 v140, v91, v92
	v_cvt_pk_bf16_f32 v141, v93, v94
	v_cvt_pk_bf16_f32 v142, v95, v96
	v_cvt_pk_bf16_f32 v143, v97, v98
	v_cvt_pk_bf16_f32 v136, v99, v68
	v_cvt_pk_bf16_f32 v137, v69, v70
	v_cvt_pk_bf16_f32 v138, v71, v72
	v_cvt_pk_bf16_f32 v139, v73, v74
	v_cvt_pk_bf16_f32 v132, v75, v76
	v_cvt_pk_bf16_f32 v133, v77, v78
	v_cvt_pk_bf16_f32 v134, v79, v80
	v_cvt_pk_bf16_f32 v135, v81, v82
	v_cvt_pk_bf16_f32 v128, v52, v53
	v_cvt_pk_bf16_f32 v129, v54, v55
	v_cvt_pk_bf16_f32 v130, v56, v57
	v_cvt_pk_bf16_f32 v131, v58, v59
	v_cvt_pk_bf16_f32 v124, v60, v61
	v_cvt_pk_bf16_f32 v125, v62, v63
	v_cvt_pk_bf16_f32 v126, v64, v65
	v_cvt_pk_bf16_f32 v127, v66, v67
	s_andn2_b64 vcc, exec, s[90:91]
	s_mov_b64 s[2:3], -1
	s_cbranch_vccnz .LBB0_996
	ds_read_b64_tr_b16 v[84:85], v190 offset:57344
	ds_read_b64_tr_b16 v[86:87], v190 offset:57856
	ds_read_b64_tr_b16 v[88:89], v190 offset:61440
	ds_read_b64_tr_b16 v[90:91], v190 offset:61952
	ds_read_b64_tr_b16 v[92:93], v190 offset:58368
	ds_read_b64_tr_b16 v[94:95], v190 offset:58880
	ds_read_b64_tr_b16 v[96:97], v190 offset:62464
	ds_read_b64_tr_b16 v[98:99], v190 offset:62976
	ds_read_b64_tr_b16 v[100:101], v190 offset:59392
	ds_read_b64_tr_b16 v[102:103], v190 offset:59904
	ds_read_b64_tr_b16 v[104:105], v190 offset:63488
	ds_read_b64_tr_b16 v[106:107], v190 offset:64000
	ds_read_b64_tr_b16 v[108:109], v190 offset:60416
	ds_read_b64_tr_b16 v[110:111], v190 offset:60928
	s_mov_b64 s[2:3], 0
	s_waitcnt lgkmcnt(10)
	v_mfma_f32_32x32x16_bf16 v[20:35], v[152:155], v[84:87], v[20:35]
	ds_read_b64_tr_b16 v[112:113], v190 offset:64512
	ds_read_b64_tr_b16 v[114:115], v190 offset:65024
	v_mfma_f32_32x32x16_bf16 v[36:51], v[152:155], v[88:91], v[36:51]
	ds_read_b64_tr_b16 v[84:85], v190 offset:49152
	ds_read_b64_tr_b16 v[86:87], v190 offset:49664
	s_waitcnt lgkmcnt(10)
	v_mfma_f32_32x32x16_bf16 v[20:35], v[148:151], v[92:95], v[20:35]
	ds_read_b64_tr_b16 v[88:89], v190 offset:53248
	ds_read_b64_tr_b16 v[90:91], v190 offset:53760
	v_mfma_f32_32x32x16_bf16 v[36:51], v[148:151], v[96:99], v[36:51]
	ds_read_b64_tr_b16 v[92:93], v190 offset:50176
	ds_read_b64_tr_b16 v[94:95], v190 offset:50688
	s_waitcnt lgkmcnt(10)
	v_mfma_f32_32x32x16_bf16 v[20:35], v[144:147], v[100:103], v[20:35]
	ds_read_b64_tr_b16 v[96:97], v190 offset:54272
	ds_read_b64_tr_b16 v[98:99], v190 offset:54784
	v_mfma_f32_32x32x16_bf16 v[36:51], v[144:147], v[104:107], v[36:51]
	ds_read_b64_tr_b16 v[100:101], v190 offset:51200
	ds_read_b64_tr_b16 v[102:103], v190 offset:51712
	s_waitcnt lgkmcnt(10)
	v_mfma_f32_32x32x16_bf16 v[20:35], v[140:143], v[108:111], v[20:35]
	ds_read_b64_tr_b16 v[104:105], v190 offset:55296
	ds_read_b64_tr_b16 v[106:107], v190 offset:55808
	v_mfma_f32_32x32x16_bf16 v[36:51], v[140:143], v[112:115], v[36:51]
	ds_read_b64_tr_b16 v[108:109], v190 offset:52224
	ds_read_b64_tr_b16 v[110:111], v190 offset:52736
	s_waitcnt lgkmcnt(10)
	v_mfma_f32_32x32x16_bf16 v[20:35], v[136:139], v[84:87], v[20:35]
	ds_read_b64_tr_b16 v[112:113], v190 offset:56320
	ds_read_b64_tr_b16 v[114:115], v190 offset:56832
	v_mfma_f32_32x32x16_bf16 v[36:51], v[136:139], v[88:91], v[36:51]
	s_waitcnt lgkmcnt(8)
	v_mfma_f32_32x32x16_bf16 v[20:35], v[132:135], v[92:95], v[20:35]
	v_mfma_f32_32x32x16_bf16 v[36:51], v[132:135], v[96:99], v[36:51]
	s_waitcnt lgkmcnt(4)
	v_mfma_f32_32x32x16_bf16 v[20:35], v[128:131], v[100:103], v[20:35]
	v_mfma_f32_32x32x16_bf16 v[36:51], v[128:131], v[104:107], v[36:51]
	s_waitcnt lgkmcnt(0)
	v_mfma_f32_32x32x16_bf16 v[20:35], v[124:127], v[108:111], v[20:35]
	v_mfma_f32_32x32x16_bf16 v[36:51], v[124:127], v[112:115], v[36:51]
	s_branch .LBB0_997
